# up-projection epilogue: the two 8-byte stores per output row (n=0, n=1) merged into one 16-byte store, n=0 halves parked in free VGPR quads
# speedup vs baseline: 1.0363x; 1.0026x over previous
; __device__ __forceinline__ unsigned cvt_pk_bf16(float lo, float hi) { unsigned r; asm volatile("v_cvt_pk_bf16_f32 %0, %1, %2" : "=v"(r) : "v"(lo), "v"(hi)); return r; }
; __device__ __forceinline__ float sigmoidf_(float x) { return __builtin_amdgcn_rcpf(1.0f + __builtin_amdgcn_exp2f(-x * LOG2E)); }
; __device__ __forceinline__ f32x4 ror1v(const f32x4 v) { return (f32x4){dpp_ror1(v[0]), dpp_ror1(v[1]), dpp_ror1(v[2]), dpp_ror1(v[3])}; }
; __device__ __forceinline__ f32x4 rol1v(const f32x4 v) { return (f32x4){dpp_rol1(v[0]), dpp_rol1(v[1]), dpp_rol1(v[2]), dpp_rol1(v[3])}; }
;     __device__ __forceinline__ void operator()(const f32x4 (&acc)[2][2][4][2], const Unit& u, int wr, int wc, int fr, int fq) const {
;     ...
;                 for (int m = 0; m < 4; ++m) {
;                     const f32x4 cg_ = acc[ai][0][m][n], cv_ = acc[ai][1][m][n];
;                     const f32x4 ug0 = m > 0 ? ror1v(acc[ai][0][m - 1][n]) : hpg, uv0 = m > 0 ? ror1v(acc[ai][1][m - 1][n]) : hpv;
;                     const f32x4 dg0 = m < 3 ? rol1v(acc[ai][0][m + 1][n]) : hng, dv0 = m < 3 ? rol1v(acc[ai][1][m + 1][n]) : hnv;
;                     const f32x4 ug1 = ror1v(cg_), uv1 = ror1v(cv_), dg1 = rol1v(cg_), dv1 = rol1v(cv_);
;                     f32x4 ug, uv, dg, dv;
; #pragma unroll
;                     for (int e = 0; e < 4; ++e) { ug[e] = fr == 0 ? ug0[e] : ug1[e]; uv[e] = fr == 0 ? uv0[e] : uv1[e]; dg[e] = fr == 15 ? dg0[e] : dg1[e]; dv[e] = fr == 15 ? dv0[e] : dv1[e]; }
;                     const f32x4 gc = w0g * ug + w1g * cg_ + w2g * dg + bg, vc = w0v * uv + w1v * cv_ + w2v * dv + bv;
;                     f32x4 r;
; #pragma unroll
;                     for (int e = 0; e < 4; ++e) r[e] = gc[e] * sigmoidf_(gc[e]) * vc[e];
;                     u32x2 w; w.x = cvt_pk_bf16(r[0], r[1]); w.y = cvt_pk_bf16(r[2], r[3]);
;                     *(u32x2*)(ACT + (size_t)(u.pm * BM + ai * HALF + wr * 64 + m * 16 + fr) * FF + ch) = w;
.LBB0_972:
	v_mov_b32_dpp v231, v130 row_ror:15 row_mask:0xf bank_mask:0xf
	v_mov_b32_dpp v235, v142 row_ror:1 row_mask:0xf bank_mask:0xf
	v_mov_b32_dpp v236, v143 row_ror:1 row_mask:0xf bank_mask:0xf
	v_mov_b32_dpp v239, v138 row_ror:1 row_mask:0xf bank_mask:0xf
	v_mov_b32_dpp v240, v139 row_ror:1 row_mask:0xf bank_mask:0xf
	v_mov_b32_dpp v190, v138 row_ror:15 row_mask:0xf bank_mask:0xf
	s_waitcnt lgkmcnt(0)
	v_cndmask_b32_e64 v193, v235, v174, s[0:1]
	v_cndmask_b32_e64 v192, v239, v170, s[0:1]
	v_cndmask_b32_e64 v196, v190, v231, s[36:37]
	s_waitcnt vmcnt(3)
	v_mov_b32_e32 v190, v166
	v_mov_b32_e32 v191, v106
	v_cndmask_b32_e64 v175, v236, v175, s[0:1]
	v_cndmask_b32_e64 v174, v240, v171, s[0:1]
	v_mov_b32_e32 v106, v167
	v_mov_b32_dpp v225, v134 row_ror:15 row_mask:0xf bank_mask:0xf
	v_mov_b32_dpp v228, v135 row_ror:15 row_mask:0xf bank_mask:0xf
	v_mov_b32_dpp v232, v131 row_ror:15 row_mask:0xf bank_mask:0xf
	v_mov_b32_dpp v0, v142 row_ror:15 row_mask:0xf bank_mask:0xf
	v_mov_b32_dpp v243, v143 row_ror:15 row_mask:0xf bank_mask:0xf
	v_mov_b32_dpp v246, v139 row_ror:15 row_mask:0xf bank_mask:0xf
	v_pk_mul_f32 v[194:195], v[190:191], v[192:193]
	v_mov_b32_e32 v226, v138
	v_mov_b32_e32 v227, v142
	s_waitcnt vmcnt(2)
	v_mov_b32_e32 v192, v162
	v_mov_b32_e32 v193, v110
	v_pk_mul_f32 v[166:167], v[106:107], v[174:175]
	v_mov_b32_e32 v142, v139
	v_mov_b32_e32 v110, v163
	v_cndmask_b32_e64 v197, v0, v225, s[36:37]
	v_pk_fma_f32 v[226:227], v[226:227], v[192:193], v[194:195]
	s_waitcnt vmcnt(1)
	v_mov_b32_e32 v194, v158
	v_mov_b32_e32 v195, v114
	v_cndmask_b32_e64 v171, v243, v228, s[36:37]
	v_cndmask_b32_e64 v170, v246, v232, s[36:37]
	v_pk_fma_f32 v[138:139], v[142:143], v[110:111], v[166:167]
	v_mov_b32_e32 v114, v159
	v_pk_fma_f32 v[226:227], v[194:195], v[196:197], v[226:227]
	v_mov_b32_e32 v197, v118
	v_pk_fma_f32 v[138:139], v[114:115], v[170:171], v[138:139]
	s_waitcnt vmcnt(0)
	v_mov_b32_e32 v118, v155
	v_pk_add_f32 v[138:139], v[118:119], v[138:139]
	v_mul_f32_e32 v142, 0xbfb8aa3b, v139
	v_exp_f32_e32 v142, v142
	v_mov_b32_dpp v237, v144 row_ror:1 row_mask:0xf bank_mask:0xf
	v_add_f32_e32 v142, 1.0, v142
	v_rcp_f32_e32 v142, v142
	v_mov_b32_dpp v241, v140 row_ror:1 row_mask:0xf bank_mask:0xf
	v_mul_f32_e32 v139, v139, v142
	v_mul_f32_e32 v170, v138, v139
	v_cndmask_b32_e64 v139, v237, v176, s[0:1]
	v_cndmask_b32_e64 v138, v241, v172, s[0:1]
	v_mov_b32_e32 v142, v168
	v_mov_b32_e32 v143, v108
	v_mov_b32_dpp v229, v136 row_ror:15 row_mask:0xf bank_mask:0xf
	v_mov_b32_dpp v233, v132 row_ror:15 row_mask:0xf bank_mask:0xf
	v_mov_b32_dpp v244, v144 row_ror:15 row_mask:0xf bank_mask:0xf
	v_mov_b32_dpp v247, v140 row_ror:15 row_mask:0xf bank_mask:0xf
	v_mov_b32_e32 v196, v154
	v_pk_mul_f32 v[138:139], v[142:143], v[138:139]
	v_mov_b32_e32 v158, v140
	v_mov_b32_e32 v159, v144
	v_mov_b32_e32 v154, v164
	v_mov_b32_e32 v155, v112
	v_cndmask_b32_e64 v163, v244, v229, s[36:37]
	v_cndmask_b32_e64 v162, v247, v233, s[36:37]
	v_pk_fma_f32 v[138:139], v[158:159], v[154:155], v[138:139]
	v_mov_b32_e32 v158, v160
	v_mov_b32_e32 v159, v116
	v_pk_fma_f32 v[138:139], v[158:159], v[162:163], v[138:139]
	v_mov_b32_e32 v162, v156
	v_mov_b32_e32 v163, v120
	v_pk_add_f32 v[138:139], v[162:163], v[138:139]
	v_mul_f32_e32 v108, 0xbfb8aa3b, v139
	v_exp_f32_e32 v108, v108
	v_mov_b32_dpp v238, v145 row_ror:1 row_mask:0xf bank_mask:0xf
	v_add_f32_e32 v108, 1.0, v108
	v_rcp_f32_e32 v108, v108
	v_mov_b32_dpp v242, v141 row_ror:1 row_mask:0xf bank_mask:0xf
	v_mul_f32_e32 v108, v139, v108
	v_mul_f32_e32 v140, v138, v108
	v_cndmask_b32_e64 v139, v238, v177, s[0:1]
	v_cndmask_b32_e64 v138, v242, v173, s[0:1]
	v_mov_b32_e32 v108, v169
	v_mov_b32_dpp v230, v137 row_ror:15 row_mask:0xf bank_mask:0xf
	v_mov_b32_dpp v234, v133 row_ror:15 row_mask:0xf bank_mask:0xf
	v_mov_b32_dpp v245, v145 row_ror:15 row_mask:0xf bank_mask:0xf
	v_mov_b32_dpp v248, v141 row_ror:15 row_mask:0xf bank_mask:0xf
	v_pk_mul_f32 v[138:139], v[108:109], v[138:139]
	v_mov_b32_e32 v144, v141
	v_mov_b32_e32 v112, v165
	v_cndmask_b32_e64 v167, v245, v230, s[36:37]
	v_cndmask_b32_e64 v166, v248, v234, s[36:37]
	v_pk_fma_f32 v[138:139], v[144:145], v[112:113], v[138:139]
	v_mov_b32_e32 v116, v161
	v_pk_add_f32 v[226:227], v[196:197], v[226:227]
	v_pk_fma_f32 v[138:139], v[116:117], v[166:167], v[138:139]
	v_mov_b32_e32 v120, v157
	v_mul_f32_e32 v0, 0xbfb8aa3b, v227
	v_pk_add_f32 v[138:139], v[120:121], v[138:139]
	v_exp_f32_e32 v0, v0
	v_mul_f32_e32 v141, 0xbfb8aa3b, v139
	v_exp_f32_e32 v141, v141
	s_lshl_b32 s20, s21, 8
	v_add_f32_e32 v0, 1.0, v0
	v_rcp_f32_e32 v0, v0
	v_add_f32_e32 v141, 1.0, v141
	v_rcp_f32_e32 v141, v141
	v_mov_b64_e32 v[144:145], s[84:85]
	v_mul_f32_e32 v0, v227, v0
	v_mul_f32_e32 v0, v226, v0
	v_mul_f32_e32 v139, v139, v141
	v_mul_f32_e32 v138, v138, v139
	v_cvt_pk_bf16_f32 v156, v0, v170
	v_add_u32_e32 v0, s20, v213
	v_cvt_pk_bf16_f32 v157, v140, v138
	v_mad_i64_i32 v[138:139], s[24:25], v0, s90, v[144:145]
	v_lshlrev_b64 v[140:141], 1, v[186:187]
	v_lshl_add_u64 v[138:139], v[138:139], 0, v[140:141]
	v_mov_b32_dpp v174, v134 row_ror:1 row_mask:0xf bank_mask:0xf
	v_mov_b32_dpp v187, v130 row_ror:1 row_mask:0xf bank_mask:0xf
	v_mov_b32_e32 v246, v156
	v_mov_b32_e32 v247, v157
	v_cndmask_b32_e64 v157, v174, v235, s[0:1]
	v_cndmask_b32_e64 v156, v187, v239, s[0:1]
	v_mov_b32_dpp v166, v126 row_ror:15 row_mask:0xf bank_mask:0xf
	v_mov_b32_dpp v170, v122 row_ror:15 row_mask:0xf bank_mask:0xf
	v_pk_mul_f32 v[156:157], v[190:191], v[156:157]
	v_mov_b32_e32 v164, v130
	v_mov_b32_e32 v165, v134
	v_cndmask_b32_e64 v161, v225, v166, s[36:37]
	v_cndmask_b32_e64 v160, v231, v170, s[36:37]
; __device__ __forceinline__ unsigned cvt_pk_bf16(float lo, float hi) { unsigned r; asm volatile("v_cvt_pk_bf16_f32 %0, %1, %2" : "=v"(r) : "v"(lo), "v"(hi)); return r; }
; __device__ __forceinline__ float sigmoidf_(float x) { return __builtin_amdgcn_rcpf(1.0f + __builtin_amdgcn_exp2f(-x * LOG2E)); }
; __device__ __forceinline__ f32x4 ror1v(const f32x4 v) { return (f32x4){dpp_ror1(v[0]), dpp_ror1(v[1]), dpp_ror1(v[2]), dpp_ror1(v[3])}; }
; __device__ __forceinline__ f32x4 rol1v(const f32x4 v) { return (f32x4){dpp_rol1(v[0]), dpp_rol1(v[1]), dpp_rol1(v[2]), dpp_rol1(v[3])}; }
;     __device__ __forceinline__ void operator()(const f32x4 (&acc)[2][2][4][2], const Unit& u, int wr, int wc, int fr, int fq) const {
;     ...
;                 for (int m = 0; m < 4; ++m) {
;                     const f32x4 cg_ = acc[ai][0][m][n], cv_ = acc[ai][1][m][n];
;                     const f32x4 ug0 = m > 0 ? ror1v(acc[ai][0][m - 1][n]) : hpg, uv0 = m > 0 ? ror1v(acc[ai][1][m - 1][n]) : hpv;
;                     const f32x4 dg0 = m < 3 ? rol1v(acc[ai][0][m + 1][n]) : hng, dv0 = m < 3 ? rol1v(acc[ai][1][m + 1][n]) : hnv;
;                     const f32x4 ug1 = ror1v(cg_), uv1 = ror1v(cv_), dg1 = rol1v(cg_), dv1 = rol1v(cv_);
;                     f32x4 ug, uv, dg, dv;
; #pragma unroll
;                     for (int e = 0; e < 4; ++e) { ug[e] = fr == 0 ? ug0[e] : ug1[e]; uv[e] = fr == 0 ? uv0[e] : uv1[e]; dg[e] = fr == 15 ? dg0[e] : dg1[e]; dv[e] = fr == 15 ? dv0[e] : dv1[e]; }
;                     const f32x4 gc = w0g * ug + w1g * cg_ + w2g * dg + bg, vc = w0v * uv + w1v * cv_ + w2v * dv + bv;
;                     f32x4 r;
; #pragma unroll
;                     for (int e = 0; e < 4; ++e) r[e] = gc[e] * sigmoidf_(gc[e]) * vc[e];
;                     u32x2 w; w.x = cvt_pk_bf16(r[0], r[1]); w.y = cvt_pk_bf16(r[2], r[3]);
;                     *(u32x2*)(ACT + (size_t)(u.pm * BM + ai * HALF + wr * 64 + m * 16 + fr) * FF + ch) = w;
	v_pk_fma_f32 v[156:157], v[164:165], v[192:193], v[156:157]
	v_pk_fma_f32 v[156:157], v[194:195], v[160:161], v[156:157]
	v_pk_add_f32 v[156:157], v[196:197], v[156:157]
	v_mov_b32_dpp v175, v135 row_ror:1 row_mask:0xf bank_mask:0xf
	v_mul_f32_e32 v130, 0xbfb8aa3b, v157
	v_exp_f32_e32 v130, v130
	v_mov_b32_dpp v226, v131 row_ror:1 row_mask:0xf bank_mask:0xf
	v_add_f32_e32 v130, 1.0, v130
	v_rcp_f32_e32 v130, v130
	v_mov_b32_dpp v167, v127 row_ror:15 row_mask:0xf bank_mask:0xf
	v_mov_b32_dpp v171, v123 row_ror:15 row_mask:0xf bank_mask:0xf
	v_mov_b32_e32 v134, v131
	v_mul_f32_e32 v130, v157, v130
	v_mul_f32_e32 v164, v156, v130
	v_cndmask_b32_e64 v157, v175, v236, s[0:1]
	v_cndmask_b32_e64 v156, v226, v240, s[0:1]
	v_pk_mul_f32 v[156:157], v[106:107], v[156:157]
	v_cndmask_b32_e64 v161, v228, v167, s[36:37]
	v_cndmask_b32_e64 v160, v232, v171, s[36:37]
	v_pk_fma_f32 v[130:131], v[134:135], v[110:111], v[156:157]
	v_pk_fma_f32 v[130:131], v[114:115], v[160:161], v[130:131]
	v_pk_add_f32 v[130:131], v[118:119], v[130:131]
	v_mov_b32_dpp v176, v136 row_ror:1 row_mask:0xf bank_mask:0xf
	v_mul_f32_e32 v134, 0xbfb8aa3b, v131
	v_exp_f32_e32 v134, v134
	v_mov_b32_dpp v227, v132 row_ror:1 row_mask:0xf bank_mask:0xf
	v_add_f32_e32 v134, 1.0, v134
	v_rcp_f32_e32 v134, v134
	v_mov_b32_dpp v168, v128 row_ror:15 row_mask:0xf bank_mask:0xf
	v_mov_b32_dpp v172, v124 row_ror:15 row_mask:0xf bank_mask:0xf
	v_mov_b32_e32 v156, v132
	v_mul_f32_e32 v131, v131, v134
	v_mul_f32_e32 v160, v130, v131
	v_cndmask_b32_e64 v131, v176, v237, s[0:1]
	v_cndmask_b32_e64 v130, v227, v241, s[0:1]
	v_pk_mul_f32 v[130:131], v[142:143], v[130:131]
	v_mov_b32_e32 v157, v136
	v_cndmask_b32_e64 v135, v229, v168, s[36:37]
	v_cndmask_b32_e64 v134, v233, v172, s[36:37]
	v_pk_fma_f32 v[130:131], v[156:157], v[154:155], v[130:131]
	v_pk_fma_f32 v[130:131], v[158:159], v[134:135], v[130:131]
	v_pk_add_f32 v[130:131], v[162:163], v[130:131]
	v_mov_b32_dpp v177, v137 row_ror:1 row_mask:0xf bank_mask:0xf
	v_mul_f32_e32 v132, 0xbfb8aa3b, v131
	v_exp_f32_e32 v132, v132
	v_mov_b32_dpp v243, v133 row_ror:1 row_mask:0xf bank_mask:0xf
	v_add_f32_e32 v132, 1.0, v132
	v_rcp_f32_e32 v132, v132
	v_mov_b32_dpp v169, v129 row_ror:15 row_mask:0xf bank_mask:0xf
	v_mov_b32_dpp v173, v125 row_ror:15 row_mask:0xf bank_mask:0xf
	v_mov_b32_e32 v136, v133
	v_mul_f32_e32 v131, v131, v132
	v_mul_f32_e32 v156, v130, v131
	v_cndmask_b32_e64 v131, v177, v238, s[0:1]
	v_cndmask_b32_e64 v130, v243, v242, s[0:1]
	v_pk_mul_f32 v[130:131], v[108:109], v[130:131]
	v_cndmask_b32_e64 v135, v230, v169, s[36:37]
	v_cndmask_b32_e64 v134, v234, v173, s[36:37]
	v_pk_fma_f32 v[130:131], v[136:137], v[112:113], v[130:131]
	v_pk_fma_f32 v[130:131], v[116:117], v[134:135], v[130:131]
	v_pk_add_f32 v[130:131], v[120:121], v[130:131]
	v_mov_b32_dpp v229, v126 row_ror:1 row_mask:0xf bank_mask:0xf
	v_mul_f32_e32 v132, 0xbfb8aa3b, v131
	v_exp_f32_e32 v132, v132
	v_mov_b32_dpp v233, v122 row_ror:1 row_mask:0xf bank_mask:0xf
	v_mov_b32_e32 v136, v122
	v_mov_b32_e32 v137, v126
	v_add_f32_e32 v132, 1.0, v132
	v_rcp_f32_e32 v132, v132
	s_nop 0
	v_mul_f32_e32 v131, v131, v132
	v_mul_f32_e32 v130, v130, v131
	v_cvt_pk_bf16_f32 v132, v164, v160
	v_cvt_pk_bf16_f32 v133, v156, v130
	v_add_u32_e32 v130, s20, v215
	v_mad_i64_i32 v[130:131], s[24:25], v130, s90, v[144:145]
	v_lshl_add_u64 v[130:131], v[130:131], 0, v[140:141]
	v_mov_b32_e32 v238, v132
	v_mov_b32_e32 v239, v133
	v_cndmask_b32_e64 v133, v229, v174, s[0:1]
	v_cndmask_b32_e64 v132, v233, v187, s[0:1]
	v_mov_b32_dpp v156, v102 row_ror:15 row_mask:0xf bank_mask:0xf
	v_mov_b32_dpp v164, v98 row_ror:15 row_mask:0xf bank_mask:0xf
	v_pk_mul_f32 v[132:133], v[190:191], v[132:133]
	v_cndmask_b32_e64 v135, v166, v156, s[36:37]
	v_cndmask_b32_e64 v134, v170, v164, s[36:37]
	v_pk_fma_f32 v[132:133], v[136:137], v[192:193], v[132:133]
	v_mov_b32_dpp v230, v127 row_ror:1 row_mask:0xf bank_mask:0xf
	v_pk_fma_f32 v[132:133], v[194:195], v[134:135], v[132:133]
	v_mov_b32_dpp v234, v123 row_ror:1 row_mask:0xf bank_mask:0xf
	v_pk_add_f32 v[132:133], v[196:197], v[132:133]
	v_mul_f32_e32 v122, 0xbfb8aa3b, v133
	v_exp_f32_e32 v122, v122
	v_mov_b32_dpp v157, v103 row_ror:15 row_mask:0xf bank_mask:0xf
	v_mov_b32_dpp v165, v99 row_ror:15 row_mask:0xf bank_mask:0xf
	v_mov_b32_e32 v126, v123
	v_add_f32_e32 v122, 1.0, v122
	v_rcp_f32_e32 v122, v122
	v_cndmask_b32_e64 v135, v167, v157, s[36:37]
	v_cndmask_b32_e64 v134, v171, v165, s[36:37]
	v_mul_f32_e32 v122, v133, v122
	v_mul_f32_e32 v136, v132, v122
	v_cndmask_b32_e64 v133, v230, v175, s[0:1]
	v_cndmask_b32_e64 v132, v234, v226, s[0:1]
	v_pk_mul_f32 v[132:133], v[106:107], v[132:133]
	v_pk_fma_f32 v[122:123], v[126:127], v[110:111], v[132:133]
	v_mov_b32_dpp v231, v128 row_ror:1 row_mask:0xf bank_mask:0xf
	v_pk_fma_f32 v[122:123], v[114:115], v[134:135], v[122:123]
	v_mov_b32_dpp v235, v124 row_ror:1 row_mask:0xf bank_mask:0xf
	v_pk_add_f32 v[122:123], v[118:119], v[122:123]
	v_mul_f32_e32 v126, 0xbfb8aa3b, v123
	v_exp_f32_e32 v126, v126
	v_mov_b32_dpp v160, v104 row_ror:15 row_mask:0xf bank_mask:0xf
	v_mov_b32_e32 v132, v124
	v_add_f32_e32 v126, 1.0, v126
	v_rcp_f32_e32 v126, v126
	v_mov_b32_dpp v225, v100 row_ror:15 row_mask:0xf bank_mask:0xf
	v_mov_b32_e32 v133, v128
	v_cndmask_b32_e64 v127, v168, v160, s[36:37]
; #define LAS __attribute__((address_space(3)))
; __device__ __forceinline__ unsigned cvt_pk_bf16(float lo, float hi) { unsigned r; asm volatile("v_cvt_pk_bf16_f32 %0, %1, %2" : "=v"(r) : "v"(lo), "v"(hi)); return r; }
; __device__ __forceinline__ float sigmoidf_(float x) { return __builtin_amdgcn_rcpf(1.0f + __builtin_amdgcn_exp2f(-x * LOG2E)); }
; __device__ __forceinline__ f32x4 ror1v(const f32x4 v) { return (f32x4){dpp_ror1(v[0]), dpp_ror1(v[1]), dpp_ror1(v[2]), dpp_ror1(v[3])}; }
;     __device__ __forceinline__ void operator()(const f32x4 (&acc)[2][2][4][2], const Unit& u, int wr, int wc, int fr, int fq) const {
;     ...
;                 const f32x4 hpg = blk > 0 ? *(const LAS f32x4*)(xl + ((blk - 1) * 2 + 1) * 256 + colw + 4 * n) : z4;
;                 const f32x4 hpv = blk > 0 ? *(const LAS f32x4*)(xl + ((blk - 1) * 2 + 1) * 256 + 128 + colw + 4 * n) : z4;
;                 const f32x4 hng = blk < 3 ? *(const LAS f32x4*)(xl + ((blk + 1) * 2 + 0) * 256 + colw + 4 * n) : z4;
;                 const f32x4 hnv = blk < 3 ? *(const LAS f32x4*)(xl + ((blk + 1) * 2 + 0) * 256 + 128 + colw + 4 * n) : z4;
;     ...
;                 for (int m = 0; m < 4; ++m) {
;                     const f32x4 cg_ = acc[ai][0][m][n], cv_ = acc[ai][1][m][n];
;                     const f32x4 ug0 = m > 0 ? ror1v(acc[ai][0][m - 1][n]) : hpg, uv0 = m > 0 ? ror1v(acc[ai][1][m - 1][n]) : hpv;
;                     const f32x4 dg0 = m < 3 ? rol1v(acc[ai][0][m + 1][n]) : hng, dv0 = m < 3 ? rol1v(acc[ai][1][m + 1][n]) : hnv;
;                     const f32x4 ug1 = ror1v(cg_), uv1 = ror1v(cv_), dg1 = rol1v(cg_), dv1 = rol1v(cv_);
;                     f32x4 ug, uv, dg, dv;
; #pragma unroll
;                     for (int e = 0; e < 4; ++e) { ug[e] = fr == 0 ? ug0[e] : ug1[e]; uv[e] = fr == 0 ? uv0[e] : uv1[e]; dg[e] = fr == 15 ? dg0[e] : dg1[e]; dv[e] = fr == 15 ? dv0[e] : dv1[e]; }
;                     const f32x4 gc = w0g * ug + w1g * cg_ + w2g * dg + bg, vc = w0v * uv + w1v * cv_ + w2v * dv + bv;
;                     f32x4 r;
; #pragma unroll
;                     for (int e = 0; e < 4; ++e) r[e] = gc[e] * sigmoidf_(gc[e]) * vc[e];
;                     u32x2 w; w.x = cvt_pk_bf16(r[0], r[1]); w.y = cvt_pk_bf16(r[2], r[3]);
;                     *(u32x2*)(ACT + (size_t)(u.pm * BM + ai * HALF + wr * 64 + m * 16 + fr) * FF + ch) = w;
	v_mul_f32_e32 v123, v123, v126
	v_mul_f32_e32 v134, v122, v123
	v_cndmask_b32_e64 v123, v231, v176, s[0:1]
	v_cndmask_b32_e64 v122, v235, v227, s[0:1]
	v_pk_mul_f32 v[122:123], v[142:143], v[122:123]
	v_cndmask_b32_e64 v126, v172, v225, s[36:37]
	v_pk_fma_f32 v[122:123], v[132:133], v[154:155], v[122:123]
	v_pk_fma_f32 v[122:123], v[158:159], v[126:127], v[122:123]
	v_pk_add_f32 v[122:123], v[162:163], v[122:123]
	v_mov_b32_dpp v232, v129 row_ror:1 row_mask:0xf bank_mask:0xf
	v_mul_f32_e32 v124, 0xbfb8aa3b, v123
	v_exp_f32_e32 v124, v124
	v_mov_b32_dpp v236, v125 row_ror:1 row_mask:0xf bank_mask:0xf
	v_add_f32_e32 v124, 1.0, v124
	v_rcp_f32_e32 v124, v124
	v_mov_b32_dpp v161, v105 row_ror:15 row_mask:0xf bank_mask:0xf
	v_mov_b32_dpp v228, v101 row_ror:15 row_mask:0xf bank_mask:0xf
	v_mov_b32_e32 v128, v125
	v_mul_f32_e32 v123, v123, v124
	v_mul_f32_e32 v124, v122, v123
	v_cndmask_b32_e64 v123, v232, v177, s[0:1]
	v_cndmask_b32_e64 v122, v236, v243, s[0:1]
	v_pk_mul_f32 v[122:123], v[108:109], v[122:123]
	v_cndmask_b32_e64 v127, v169, v161, s[36:37]
	v_cndmask_b32_e64 v126, v173, v228, s[36:37]
	v_pk_fma_f32 v[122:123], v[128:129], v[112:113], v[122:123]
	v_pk_fma_f32 v[122:123], v[116:117], v[126:127], v[122:123]
	v_mov_b32_e32 v126, v98
	v_pk_add_f32 v[122:123], v[120:121], v[122:123]
	v_mov_b32_e32 v127, v102
	v_mul_f32_e32 v125, 0xbfb8aa3b, v123
	v_exp_f32_e32 v125, v125
	v_mov_b32_dpp v128, v103 row_ror:1 row_mask:0xf bank_mask:0xf
	v_add_f32_e32 v125, 1.0, v125
	v_rcp_f32_e32 v125, v125
	v_mov_b32_dpp v135, v99 row_ror:1 row_mask:0xf bank_mask:0xf
	v_mov_b32_dpp v129, v104 row_ror:1 row_mask:0xf bank_mask:0xf
	v_mul_f32_e32 v123, v123, v125
	v_mul_f32_e32 v123, v122, v123
	v_cvt_pk_bf16_f32 v122, v136, v134
	v_cvt_pk_bf16_f32 v123, v124, v123
	v_add_u32_e32 v124, s20, v216
	v_mad_i64_i32 v[124:125], s[24:25], v124, s90, v[144:145]
	v_lshl_add_u64 v[132:133], v[124:125], 0, v[140:141]
	v_mov_b32_e32 v242, v122
	v_mov_b32_e32 v243, v123
	v_cndmask_b32_e64 v125, v156, v150, s[36:37]
	v_mov_b32_dpp v122, v102 row_ror:1 row_mask:0xf bank_mask:0xf
	v_mov_b32_dpp v124, v98 row_ror:1 row_mask:0xf bank_mask:0xf
	v_cndmask_b32_e64 v123, v122, v229, s[0:1]
	v_cndmask_b32_e64 v122, v124, v233, s[0:1]
	v_pk_mul_f32 v[122:123], v[190:191], v[122:123]
	v_cndmask_b32_e64 v124, v164, v146, s[36:37]
	v_pk_fma_f32 v[122:123], v[126:127], v[192:193], v[122:123]
	v_mov_b32_e32 v102, v99
	v_pk_fma_f32 v[122:123], v[194:195], v[124:125], v[122:123]
	v_cndmask_b32_e64 v125, v157, v151, s[36:37]
	v_pk_add_f32 v[122:123], v[196:197], v[122:123]
	v_cndmask_b32_e64 v124, v165, v147, s[36:37]
	v_mul_f32_e32 v98, 0xbfb8aa3b, v123
	v_exp_f32_e32 v98, v98
	v_mov_b32_dpp v137, v101 row_ror:1 row_mask:0xf bank_mask:0xf
	v_add_f32_e32 v98, 1.0, v98
	v_rcp_f32_e32 v98, v98
	v_mov_b32_dpp v136, v100 row_ror:1 row_mask:0xf bank_mask:0xf
	v_mov_b32_dpp v134, v105 row_ror:1 row_mask:0xf bank_mask:0xf
	v_mul_f32_e32 v98, v123, v98
	v_mul_f32_e32 v126, v122, v98
	v_cndmask_b32_e64 v123, v128, v230, s[0:1]
	v_cndmask_b32_e64 v122, v135, v234, s[0:1]
	v_pk_mul_f32 v[122:123], v[106:107], v[122:123]
	s_andn2_b64 vcc, exec, s[16:17]
	v_pk_fma_f32 v[98:99], v[102:103], v[110:111], v[122:123]
	v_mov_b32_e32 v122, v100
	v_pk_fma_f32 v[98:99], v[114:115], v[124:125], v[98:99]
	v_mov_b32_e32 v123, v104
	v_pk_add_f32 v[98:99], v[118:119], v[98:99]
	v_cndmask_b32_e64 v103, v160, v152, s[36:37]
	v_mul_f32_e32 v102, 0xbfb8aa3b, v99
	v_exp_f32_e32 v102, v102
	v_mov_b32_e32 v104, v101
	v_mov_b32_e32 v127, 0
	v_mov_b32_e32 v128, 0
	v_add_f32_e32 v102, 1.0, v102
	v_rcp_f32_e32 v102, v102
	s_nop 0
	v_mul_f32_e32 v99, v99, v102
	v_mul_f32_e32 v124, v98, v99
	v_cndmask_b32_e64 v99, v129, v231, s[0:1]
	v_cndmask_b32_e64 v98, v136, v235, s[0:1]
	v_pk_mul_f32 v[98:99], v[142:143], v[98:99]
	v_cndmask_b32_e64 v102, v225, v148, s[36:37]
	v_pk_fma_f32 v[98:99], v[122:123], v[154:155], v[98:99]
	v_mov_b32_e32 v122, 0
	v_pk_fma_f32 v[98:99], v[158:159], v[102:103], v[98:99]
	v_cndmask_b32_e64 v103, v161, v153, s[36:37]
	v_pk_add_f32 v[98:99], v[162:163], v[98:99]
	v_cndmask_b32_e64 v102, v228, v149, s[36:37]
	v_mul_f32_e32 v100, 0xbfb8aa3b, v99
	v_exp_f32_e32 v100, v100
	v_mov_b32_e32 v129, 0
	v_add_f32_e32 v100, 1.0, v100
	v_rcp_f32_e32 v100, v100
	s_nop 0
	v_mul_f32_e32 v99, v99, v100
	v_mul_f32_e32 v100, v98, v99
	v_cndmask_b32_e64 v99, v134, v232, s[0:1]
	v_cndmask_b32_e64 v98, v137, v236, s[0:1]
	v_pk_mul_f32 v[98:99], v[108:109], v[98:99]
	s_nop 0
	v_pk_fma_f32 v[98:99], v[104:105], v[112:113], v[98:99]
	s_nop 0
	v_pk_fma_f32 v[98:99], v[116:117], v[102:103], v[98:99]
	s_nop 0
	v_pk_add_f32 v[98:99], v[120:121], v[98:99]
	s_nop 0
	v_mul_f32_e32 v101, 0xbfb8aa3b, v99
	v_exp_f32_e32 v101, v101
	s_nop 0
	v_add_f32_e32 v101, 1.0, v101
	v_rcp_f32_e32 v101, v101
	s_nop 0
	v_mul_f32_e32 v99, v99, v101
	v_mul_f32_e32 v99, v98, v99
	v_cvt_pk_bf16_f32 v98, v126, v124
	v_cvt_pk_bf16_f32 v99, v100, v99
	v_add_u32_e32 v100, s20, v217
	v_mad_i64_i32 v[100:101], s[20:21], v100, s90, v[144:145]
	v_lshl_add_u64 v[134:135], v[100:101], 0, v[140:141]
	v_mov_b32_e32 v234, v98
	v_mov_b32_e32 v235, v99
	v_cndmask_b32_e64 v98, 0, 1, s[16:17]
	v_cmp_ne_u32_e64 s[46:47], 1, v98
	v_mov_b32_e32 v126, 0
	s_cbranch_vccnz .LBB0_974
	ds_read_b128 v[126:129], v218 offset:3072

; __device__ __forceinline__ unsigned cvt_pk_bf16(float lo, float hi) { unsigned r; asm volatile("v_cvt_pk_bf16_f32 %0, %1, %2" : "=v"(r) : "v"(lo), "v"(hi)); return r; }
; __device__ __forceinline__ float sigmoidf_(float x) { return __builtin_amdgcn_rcpf(1.0f + __builtin_amdgcn_exp2f(-x * LOG2E)); }
; __device__ __forceinline__ f32x4 ror1v(const f32x4 v) { return (f32x4){dpp_ror1(v[0]), dpp_ror1(v[1]), dpp_ror1(v[2]), dpp_ror1(v[3])}; }
; __device__ __forceinline__ f32x4 rol1v(const f32x4 v) { return (f32x4){dpp_rol1(v[0]), dpp_rol1(v[1]), dpp_rol1(v[2]), dpp_rol1(v[3])}; }
;     __device__ __forceinline__ void operator()(const f32x4 (&acc)[2][2][4][2], const Unit& u, int wr, int wc, int fr, int fq) const {
;     ...
;                 for (int m = 0; m < 4; ++m) {
;                     const f32x4 cg_ = acc[ai][0][m][n], cv_ = acc[ai][1][m][n];
;                     const f32x4 ug0 = m > 0 ? ror1v(acc[ai][0][m - 1][n]) : hpg, uv0 = m > 0 ? ror1v(acc[ai][1][m - 1][n]) : hpv;
;                     const f32x4 dg0 = m < 3 ? rol1v(acc[ai][0][m + 1][n]) : hng, dv0 = m < 3 ? rol1v(acc[ai][1][m + 1][n]) : hnv;
;                     const f32x4 ug1 = ror1v(cg_), uv1 = ror1v(cv_), dg1 = rol1v(cg_), dv1 = rol1v(cv_);
;                     f32x4 ug, uv, dg, dv;
; #pragma unroll
;                     for (int e = 0; e < 4; ++e) { ug[e] = fr == 0 ? ug0[e] : ug1[e]; uv[e] = fr == 0 ? uv0[e] : uv1[e]; dg[e] = fr == 15 ? dg0[e] : dg1[e]; dv[e] = fr == 15 ? dv0[e] : dv1[e]; }
;                     const f32x4 gc = w0g * ug + w1g * cg_ + w2g * dg + bg, vc = w0v * uv + w1v * cv_ + w2v * dv + bv;
;                     f32x4 r;
; #pragma unroll
;                     for (int e = 0; e < 4; ++e) r[e] = gc[e] * sigmoidf_(gc[e]) * vc[e];
;                     u32x2 w; w.x = cvt_pk_bf16(r[0], r[1]); w.y = cvt_pk_bf16(r[2], r[3]);
;                     *(u32x2*)(ACT + (size_t)(u.pm * BM + ai * HALF + wr * 64 + m * 16 + fr) * FF + ch) = w;
.LBB0_980:
	v_mov_b32_dpp v160, v94 row_ror:1 row_mask:0xf bank_mask:0xf
	v_mov_b32_dpp v166, v90 row_ror:1 row_mask:0xf bank_mask:0xf
	v_mov_b32_dpp v148, v86 row_ror:15 row_mask:0xf bank_mask:0xf
	v_mov_b32_dpp v152, v82 row_ror:15 row_mask:0xf bank_mask:0xf
	v_mov_b32_dpp v144, v94 row_ror:15 row_mask:0xf bank_mask:0xf
	v_mov_b32_dpp v146, v90 row_ror:15 row_mask:0xf bank_mask:0xf
	s_waitcnt lgkmcnt(0)
	v_cndmask_b32_e64 v137, v160, v126, s[0:1]
	v_cndmask_b32_e64 v136, v166, v122, s[0:1]
	v_cndmask_b32_e64 v145, v144, v148, s[36:37]
	v_cndmask_b32_e64 v144, v146, v152, s[36:37]
	v_pk_mul_f32 v[136:137], v[190:191], v[136:137]
	v_mov_b32_e32 v146, v90
	v_mov_b32_e32 v147, v94
	v_pk_fma_f32 v[136:137], v[146:147], v[192:193], v[136:137]
	v_pk_fma_f32 v[136:137], v[194:195], v[144:145], v[136:137]
	v_pk_add_f32 v[136:137], v[196:197], v[136:137]
	v_mov_b32_dpp v161, v95 row_ror:1 row_mask:0xf bank_mask:0xf
	v_mul_f32_e32 v90, 0xbfb8aa3b, v137
	v_exp_f32_e32 v90, v90
	v_mov_b32_dpp v167, v91 row_ror:1 row_mask:0xf bank_mask:0xf
	v_add_f32_e32 v90, 1.0, v90
	v_rcp_f32_e32 v90, v90
	v_cndmask_b32_e64 v127, v161, v127, s[0:1]
	v_cndmask_b32_e64 v126, v167, v123, s[0:1]
	v_mov_b32_dpp v149, v87 row_ror:15 row_mask:0xf bank_mask:0xf
	v_mov_b32_dpp v153, v83 row_ror:15 row_mask:0xf bank_mask:0xf
	v_mov_b32_dpp v170, v95 row_ror:15 row_mask:0xf bank_mask:0xf
	v_mov_b32_dpp v173, v91 row_ror:15 row_mask:0xf bank_mask:0xf
	v_mul_f32_e32 v90, v137, v90
	v_pk_mul_f32 v[126:127], v[106:107], v[126:127]
	v_mov_b32_e32 v94, v91
	v_mul_f32_e32 v136, v136, v90
	v_cndmask_b32_e64 v123, v170, v149, s[36:37]
	v_cndmask_b32_e64 v122, v173, v153, s[36:37]
	v_pk_fma_f32 v[90:91], v[94:95], v[110:111], v[126:127]
	v_pk_fma_f32 v[90:91], v[114:115], v[122:123], v[90:91]
	v_pk_add_f32 v[90:91], v[118:119], v[90:91]
	v_mov_b32_dpp v164, v96 row_ror:1 row_mask:0xf bank_mask:0xf
	v_mul_f32_e32 v94, 0xbfb8aa3b, v91
	v_exp_f32_e32 v94, v94
	v_mov_b32_dpp v168, v92 row_ror:1 row_mask:0xf bank_mask:0xf
	v_add_f32_e32 v94, 1.0, v94
	v_rcp_f32_e32 v94, v94
	v_mov_b32_dpp v150, v88 row_ror:15 row_mask:0xf bank_mask:0xf
	v_mul_f32_e32 v91, v91, v94
	v_mul_f32_e32 v126, v90, v91
	v_cndmask_b32_e64 v91, v164, v128, s[0:1]
	v_cndmask_b32_e64 v90, v168, v124, s[0:1]
	v_mov_b32_dpp v156, v84 row_ror:15 row_mask:0xf bank_mask:0xf
	v_mov_b32_dpp v171, v96 row_ror:15 row_mask:0xf bank_mask:0xf
	v_mov_b32_dpp v174, v92 row_ror:15 row_mask:0xf bank_mask:0xf
	v_pk_mul_f32 v[90:91], v[142:143], v[90:91]
	v_mov_b32_e32 v122, v92
	v_mov_b32_e32 v123, v96
	v_cndmask_b32_e64 v95, v171, v150, s[36:37]
	v_cndmask_b32_e64 v94, v174, v156, s[36:37]
	v_pk_fma_f32 v[90:91], v[122:123], v[154:155], v[90:91]
	v_pk_fma_f32 v[90:91], v[158:159], v[94:95], v[90:91]
	v_pk_add_f32 v[90:91], v[162:163], v[90:91]
	v_mov_b32_dpp v165, v97 row_ror:1 row_mask:0xf bank_mask:0xf
	v_mul_f32_e32 v92, 0xbfb8aa3b, v91
	v_exp_f32_e32 v92, v92
	v_mov_b32_dpp v169, v93 row_ror:1 row_mask:0xf bank_mask:0xf
	v_add_f32_e32 v92, 1.0, v92
	v_rcp_f32_e32 v92, v92
	v_mov_b32_dpp v151, v89 row_ror:15 row_mask:0xf bank_mask:0xf
	v_mul_f32_e32 v91, v91, v92
	v_mul_f32_e32 v122, v90, v91
	v_cndmask_b32_e64 v91, v165, v129, s[0:1]
	v_cndmask_b32_e64 v90, v169, v125, s[0:1]
	v_mov_b32_dpp v157, v85 row_ror:15 row_mask:0xf bank_mask:0xf
	v_mov_b32_dpp v172, v97 row_ror:15 row_mask:0xf bank_mask:0xf
	v_mov_b32_dpp v175, v93 row_ror:15 row_mask:0xf bank_mask:0xf
	v_pk_mul_f32 v[90:91], v[108:109], v[90:91]
	v_mov_b32_e32 v96, v93
	v_cndmask_b32_e64 v95, v172, v151, s[36:37]
	v_cndmask_b32_e64 v94, v175, v157, s[36:37]
	v_pk_fma_f32 v[90:91], v[96:97], v[112:113], v[90:91]
	v_pk_fma_f32 v[90:91], v[116:117], v[94:95], v[90:91]
	v_add_u32_e32 v94, 0x80, v0
	v_pk_add_f32 v[90:91], v[120:121], v[90:91]
	v_mul_f32_e32 v92, 0xbfb8aa3b, v91
	v_exp_f32_e32 v92, v92
	v_mov_b32_dpp v146, v86 row_ror:1 row_mask:0xf bank_mask:0xf
	v_mov_b32_dpp v172, v82 row_ror:1 row_mask:0xf bank_mask:0xf
	v_mov_b32_e32 v96, v82
	v_add_f32_e32 v92, 1.0, v92
	v_rcp_f32_e32 v92, v92
	v_mov_b32_e32 v97, v86
	v_mul_f32_e32 v91, v91, v92
	v_mul_f32_e32 v90, v90, v91
	v_cvt_pk_bf16_f32 v92, v136, v126
	v_cvt_pk_bf16_f32 v93, v122, v90
	v_mov_b64_e32 v[90:91], s[84:85]
	v_mad_i64_i32 v[94:95], s[20:21], v94, s90, v[90:91]
	v_lshl_add_u64 v[122:123], v[94:95], 0, v[140:141]
	v_mov_b32_e32 v230, v92
	v_mov_b32_e32 v231, v93
	v_cndmask_b32_e64 v93, v146, v160, s[0:1]
	v_cndmask_b32_e64 v92, v172, v166, s[0:1]
	v_mov_b32_dpp v126, v78 row_ror:15 row_mask:0xf bank_mask:0xf
	v_mov_b32_dpp v136, v74 row_ror:15 row_mask:0xf bank_mask:0xf
	v_pk_mul_f32 v[92:93], v[190:191], v[92:93]
	v_cndmask_b32_e64 v95, v148, v126, s[36:37]
	v_cndmask_b32_e64 v94, v152, v136, s[36:37]
	v_pk_fma_f32 v[92:93], v[96:97], v[192:193], v[92:93]
	v_mov_b32_dpp v147, v87 row_ror:1 row_mask:0xf bank_mask:0xf
	v_pk_fma_f32 v[92:93], v[194:195], v[94:95], v[92:93]
	v_mov_b32_dpp v173, v83 row_ror:1 row_mask:0xf bank_mask:0xf
	v_pk_add_f32 v[92:93], v[196:197], v[92:93]
	v_mul_f32_e32 v82, 0xbfb8aa3b, v93
	v_exp_f32_e32 v82, v82
	v_mov_b32_dpp v127, v79 row_ror:15 row_mask:0xf bank_mask:0xf
	v_mov_b32_e32 v86, v83
	v_add_f32_e32 v82, 1.0, v82
	v_rcp_f32_e32 v82, v82
	v_mov_b32_dpp v137, v75 row_ror:15 row_mask:0xf bank_mask:0xf
	v_cndmask_b32_e64 v95, v149, v127, s[36:37]
	v_cndmask_b32_e64 v94, v153, v137, s[36:37]
	v_mul_f32_e32 v82, v93, v82
	v_mul_f32_e32 v96, v92, v82
	v_cndmask_b32_e64 v93, v147, v161, s[0:1]
	v_cndmask_b32_e64 v92, v173, v167, s[0:1]
	v_pk_mul_f32 v[92:93], v[106:107], v[92:93]
	v_pk_fma_f32 v[82:83], v[86:87], v[110:111], v[92:93]
	v_pk_fma_f32 v[82:83], v[114:115], v[94:95], v[82:83]
; __device__ __forceinline__ unsigned cvt_pk_bf16(float lo, float hi) { unsigned r; asm volatile("v_cvt_pk_bf16_f32 %0, %1, %2" : "=v"(r) : "v"(lo), "v"(hi)); return r; }
; __device__ __forceinline__ float sigmoidf_(float x) { return __builtin_amdgcn_rcpf(1.0f + __builtin_amdgcn_exp2f(-x * LOG2E)); }
; __device__ __forceinline__ f32x4 ror1v(const f32x4 v) { return (f32x4){dpp_ror1(v[0]), dpp_ror1(v[1]), dpp_ror1(v[2]), dpp_ror1(v[3])}; }
; __device__ __forceinline__ f32x4 rol1v(const f32x4 v) { return (f32x4){dpp_rol1(v[0]), dpp_rol1(v[1]), dpp_rol1(v[2]), dpp_rol1(v[3])}; }
;     __device__ __forceinline__ void operator()(const f32x4 (&acc)[2][2][4][2], const Unit& u, int wr, int wc, int fr, int fq) const {
;     ...
;                 for (int m = 0; m < 4; ++m) {
;                     const f32x4 cg_ = acc[ai][0][m][n], cv_ = acc[ai][1][m][n];
;                     const f32x4 ug0 = m > 0 ? ror1v(acc[ai][0][m - 1][n]) : hpg, uv0 = m > 0 ? ror1v(acc[ai][1][m - 1][n]) : hpv;
;                     const f32x4 dg0 = m < 3 ? rol1v(acc[ai][0][m + 1][n]) : hng, dv0 = m < 3 ? rol1v(acc[ai][1][m + 1][n]) : hnv;
;                     const f32x4 ug1 = ror1v(cg_), uv1 = ror1v(cv_), dg1 = rol1v(cg_), dv1 = rol1v(cv_);
;                     f32x4 ug, uv, dg, dv;
; #pragma unroll
;                     for (int e = 0; e < 4; ++e) { ug[e] = fr == 0 ? ug0[e] : ug1[e]; uv[e] = fr == 0 ? uv0[e] : uv1[e]; dg[e] = fr == 15 ? dg0[e] : dg1[e]; dv[e] = fr == 15 ? dv0[e] : dv1[e]; }
;                     const f32x4 gc = w0g * ug + w1g * cg_ + w2g * dg + bg, vc = w0v * uv + w1v * cv_ + w2v * dv + bv;
;                     f32x4 r;
; #pragma unroll
;                     for (int e = 0; e < 4; ++e) r[e] = gc[e] * sigmoidf_(gc[e]) * vc[e];
;                     u32x2 w; w.x = cvt_pk_bf16(r[0], r[1]); w.y = cvt_pk_bf16(r[2], r[3]);
;                     *(u32x2*)(ACT + (size_t)(u.pm * BM + ai * HALF + wr * 64 + m * 16 + fr) * FF + ch) = w;
	v_mov_b32_dpp v170, v88 row_ror:1 row_mask:0xf bank_mask:0xf
	v_pk_add_f32 v[82:83], v[118:119], v[82:83]
	v_mov_b32_dpp v174, v84 row_ror:1 row_mask:0xf bank_mask:0xf
	v_mul_f32_e32 v86, 0xbfb8aa3b, v83
	v_exp_f32_e32 v86, v86
	v_mov_b32_e32 v92, v84
	v_add_f32_e32 v86, 1.0, v86
	v_rcp_f32_e32 v86, v86
	v_mov_b32_dpp v128, v80 row_ror:15 row_mask:0xf bank_mask:0xf
	v_mov_b32_dpp v144, v76 row_ror:15 row_mask:0xf bank_mask:0xf
	v_mov_b32_e32 v93, v88
	v_mul_f32_e32 v83, v83, v86
	v_mul_f32_e32 v94, v82, v83
	v_cndmask_b32_e64 v83, v170, v164, s[0:1]
	v_cndmask_b32_e64 v82, v174, v168, s[0:1]
	v_pk_mul_f32 v[82:83], v[142:143], v[82:83]
	v_cndmask_b32_e64 v87, v150, v128, s[36:37]
	v_cndmask_b32_e64 v86, v156, v144, s[36:37]
	v_pk_fma_f32 v[82:83], v[92:93], v[154:155], v[82:83]
	v_pk_fma_f32 v[82:83], v[158:159], v[86:87], v[82:83]
	v_pk_add_f32 v[82:83], v[162:163], v[82:83]
	v_mov_b32_dpp v171, v89 row_ror:1 row_mask:0xf bank_mask:0xf
	v_mul_f32_e32 v84, 0xbfb8aa3b, v83
	v_exp_f32_e32 v84, v84
	v_mov_b32_dpp v175, v85 row_ror:1 row_mask:0xf bank_mask:0xf
	v_add_f32_e32 v84, 1.0, v84
	v_rcp_f32_e32 v84, v84
	v_mov_b32_dpp v129, v81 row_ror:15 row_mask:0xf bank_mask:0xf
	v_mov_b32_dpp v145, v77 row_ror:15 row_mask:0xf bank_mask:0xf
	v_mov_b32_e32 v88, v85
	v_mul_f32_e32 v83, v83, v84
	v_mul_f32_e32 v84, v82, v83
	v_cndmask_b32_e64 v83, v171, v165, s[0:1]
	v_cndmask_b32_e64 v82, v175, v169, s[0:1]
	v_pk_mul_f32 v[82:83], v[108:109], v[82:83]
	v_cndmask_b32_e64 v87, v151, v129, s[36:37]
	v_cndmask_b32_e64 v86, v157, v145, s[36:37]
	v_pk_fma_f32 v[82:83], v[88:89], v[112:113], v[82:83]
	v_pk_fma_f32 v[82:83], v[116:117], v[86:87], v[82:83]
	v_pk_add_f32 v[82:83], v[120:121], v[82:83]
	v_mov_b32_dpp v148, v78 row_ror:1 row_mask:0xf bank_mask:0xf
	v_mul_f32_e32 v85, 0xbfb8aa3b, v83
	v_exp_f32_e32 v85, v85
	v_mov_b32_dpp v152, v74 row_ror:1 row_mask:0xf bank_mask:0xf
	v_mov_b32_e32 v86, v74
	v_add_f32_e32 v85, 1.0, v85
	v_rcp_f32_e32 v85, v85
	v_mov_b32_dpp v88, v70 row_ror:15 row_mask:0xf bank_mask:0xf
	v_mov_b32_e32 v87, v78
	v_mul_f32_e32 v83, v83, v85
	v_mul_f32_e32 v83, v82, v83
	v_cvt_pk_bf16_f32 v82, v96, v94
	v_cvt_pk_bf16_f32 v83, v84, v83
	v_add_u32_e32 v84, 0x90, v0
	v_mad_i64_i32 v[84:85], s[20:21], v84, s90, v[90:91]
	v_lshl_add_u64 v[124:125], v[84:85], 0, v[140:141]
	v_mov_b32_e32 v226, v82
	v_mov_b32_e32 v227, v83
	v_cndmask_b32_e64 v83, v148, v146, s[0:1]
	v_cndmask_b32_e64 v82, v152, v172, s[0:1]
	v_mov_b32_dpp v94, v66 row_ror:15 row_mask:0xf bank_mask:0xf
	v_pk_mul_f32 v[82:83], v[190:191], v[82:83]
	v_cndmask_b32_e64 v85, v126, v88, s[36:37]
	v_cndmask_b32_e64 v84, v136, v94, s[36:37]
	v_pk_fma_f32 v[82:83], v[86:87], v[192:193], v[82:83]
	v_pk_fma_f32 v[82:83], v[194:195], v[84:85], v[82:83]
	v_mov_b32_dpp v149, v79 row_ror:1 row_mask:0xf bank_mask:0xf
	v_pk_add_f32 v[82:83], v[196:197], v[82:83]
	v_mov_b32_dpp v153, v75 row_ror:1 row_mask:0xf bank_mask:0xf
	v_mul_f32_e32 v74, 0xbfb8aa3b, v83
	v_exp_f32_e32 v74, v74
	v_mov_b32_e32 v78, v75
	v_add_f32_e32 v74, 1.0, v74
	v_rcp_f32_e32 v74, v74
	v_mov_b32_dpp v89, v71 row_ror:15 row_mask:0xf bank_mask:0xf
	v_mov_b32_dpp v95, v67 row_ror:15 row_mask:0xf bank_mask:0xf
	v_cndmask_b32_e64 v85, v127, v89, s[36:37]
	v_mul_f32_e32 v74, v83, v74
	v_mul_f32_e32 v86, v82, v74
	v_cndmask_b32_e64 v83, v149, v147, s[0:1]
	v_cndmask_b32_e64 v82, v153, v173, s[0:1]
	v_pk_mul_f32 v[82:83], v[106:107], v[82:83]
	v_cndmask_b32_e64 v84, v137, v95, s[36:37]
	v_pk_fma_f32 v[74:75], v[78:79], v[110:111], v[82:83]
	v_pk_fma_f32 v[74:75], v[114:115], v[84:85], v[74:75]
	v_pk_add_f32 v[74:75], v[118:119], v[74:75]
	v_mov_b32_dpp v150, v80 row_ror:1 row_mask:0xf bank_mask:0xf
	v_mul_f32_e32 v78, 0xbfb8aa3b, v75
	v_exp_f32_e32 v78, v78
	v_mov_b32_dpp v156, v76 row_ror:1 row_mask:0xf bank_mask:0xf
	v_add_f32_e32 v78, 1.0, v78
	v_rcp_f32_e32 v78, v78
	v_mov_b32_dpp v92, v72 row_ror:15 row_mask:0xf bank_mask:0xf
	v_mov_b32_dpp v96, v68 row_ror:15 row_mask:0xf bank_mask:0xf
	v_mov_b32_e32 v82, v76
	v_mul_f32_e32 v75, v75, v78
	v_mul_f32_e32 v84, v74, v75
	v_cndmask_b32_e64 v75, v150, v170, s[0:1]
	v_cndmask_b32_e64 v74, v156, v174, s[0:1]
	v_pk_mul_f32 v[74:75], v[142:143], v[74:75]
	v_mov_b32_e32 v83, v80
	v_cndmask_b32_e64 v79, v128, v92, s[36:37]
	v_cndmask_b32_e64 v78, v144, v96, s[36:37]
	v_pk_fma_f32 v[74:75], v[82:83], v[154:155], v[74:75]
	v_pk_fma_f32 v[74:75], v[158:159], v[78:79], v[74:75]
	v_pk_add_f32 v[74:75], v[162:163], v[74:75]
	v_mov_b32_dpp v151, v81 row_ror:1 row_mask:0xf bank_mask:0xf
	v_mul_f32_e32 v76, 0xbfb8aa3b, v75
	v_exp_f32_e32 v76, v76
	v_mov_b32_dpp v157, v77 row_ror:1 row_mask:0xf bank_mask:0xf
	v_add_f32_e32 v76, 1.0, v76
	v_rcp_f32_e32 v76, v76
	v_mov_b32_dpp v93, v73 row_ror:15 row_mask:0xf bank_mask:0xf
	v_mov_b32_dpp v97, v69 row_ror:15 row_mask:0xf bank_mask:0xf
	v_mov_b32_e32 v80, v77
	v_mul_f32_e32 v75, v75, v76
	v_mul_f32_e32 v76, v74, v75
; __device__ __forceinline__ unsigned cvt_pk_bf16(float lo, float hi) { unsigned r; asm volatile("v_cvt_pk_bf16_f32 %0, %1, %2" : "=v"(r) : "v"(lo), "v"(hi)); return r; }
; __device__ __forceinline__ float sigmoidf_(float x) { return __builtin_amdgcn_rcpf(1.0f + __builtin_amdgcn_exp2f(-x * LOG2E)); }
; __device__ __forceinline__ f32x4 ror1v(const f32x4 v) { return (f32x4){dpp_ror1(v[0]), dpp_ror1(v[1]), dpp_ror1(v[2]), dpp_ror1(v[3])}; }
; __device__ __forceinline__ f32x4 rol1v(const f32x4 v) { return (f32x4){dpp_rol1(v[0]), dpp_rol1(v[1]), dpp_rol1(v[2]), dpp_rol1(v[3])}; }
;     __device__ __forceinline__ void operator()(const f32x4 (&acc)[2][2][4][2], const Unit& u, int wr, int wc, int fr, int fq) const {
;     ...
;             const int ch = 128 * u.pn + colw + 4 * n;
;             const f32x4 w0g = *(const f32x4*)(cw + ch), w1g = *(const f32x4*)(cw + FF2 + ch), w2g = *(const f32x4*)(cw + 2 * FF2 + ch), bg = *(const f32x4*)(cb + ch);
;             const f32x4 w0v = *(const f32x4*)(cw + FF + ch), w1v = *(const f32x4*)(cw + FF2 + FF + ch), w2v = *(const f32x4*)(cw + 2 * FF2 + FF + ch), bv = *(const f32x4*)(cb + FF + ch);
;     ...
;                 for (int m = 0; m < 4; ++m) {
;                     const f32x4 cg_ = acc[ai][0][m][n], cv_ = acc[ai][1][m][n];
;                     const f32x4 ug0 = m > 0 ? ror1v(acc[ai][0][m - 1][n]) : hpg, uv0 = m > 0 ? ror1v(acc[ai][1][m - 1][n]) : hpv;
;                     const f32x4 dg0 = m < 3 ? rol1v(acc[ai][0][m + 1][n]) : hng, dv0 = m < 3 ? rol1v(acc[ai][1][m + 1][n]) : hnv;
;                     const f32x4 ug1 = ror1v(cg_), uv1 = ror1v(cv_), dg1 = rol1v(cg_), dv1 = rol1v(cv_);
;                     f32x4 ug, uv, dg, dv;
; #pragma unroll
;                     for (int e = 0; e < 4; ++e) { ug[e] = fr == 0 ? ug0[e] : ug1[e]; uv[e] = fr == 0 ? uv0[e] : uv1[e]; dg[e] = fr == 15 ? dg0[e] : dg1[e]; dv[e] = fr == 15 ? dv0[e] : dv1[e]; }
;                     const f32x4 gc = w0g * ug + w1g * cg_ + w2g * dg + bg, vc = w0v * uv + w1v * cv_ + w2v * dv + bv;
;                     f32x4 r;
; #pragma unroll
;                     for (int e = 0; e < 4; ++e) r[e] = gc[e] * sigmoidf_(gc[e]) * vc[e];
;                     u32x2 w; w.x = cvt_pk_bf16(r[0], r[1]); w.y = cvt_pk_bf16(r[2], r[3]);
;                     *(u32x2*)(ACT + (size_t)(u.pm * BM + ai * HALF + wr * 64 + m * 16 + fr) * FF + ch) = w;
	v_cndmask_b32_e64 v75, v151, v171, s[0:1]
	v_cndmask_b32_e64 v74, v157, v175, s[0:1]
	v_pk_mul_f32 v[74:75], v[108:109], v[74:75]
	v_cndmask_b32_e64 v79, v129, v93, s[36:37]
	v_cndmask_b32_e64 v78, v145, v97, s[36:37]
	v_pk_fma_f32 v[74:75], v[80:81], v[112:113], v[74:75]
	v_pk_fma_f32 v[74:75], v[116:117], v[78:79], v[74:75]
	v_mov_b32_e32 v78, v66
	v_pk_add_f32 v[74:75], v[120:121], v[74:75]
	v_mov_b32_e32 v79, v70
	v_mul_f32_e32 v77, 0xbfb8aa3b, v75
	v_exp_f32_e32 v77, v77
	v_mov_b32_dpp v80, v71 row_ror:1 row_mask:0xf bank_mask:0xf
	v_add_f32_e32 v77, 1.0, v77
	v_rcp_f32_e32 v77, v77
	v_mov_b32_dpp v83, v67 row_ror:1 row_mask:0xf bank_mask:0xf
	v_mov_b32_dpp v81, v72 row_ror:1 row_mask:0xf bank_mask:0xf
	v_mul_f32_e32 v75, v75, v77
	v_mul_f32_e32 v75, v74, v75
	v_cvt_pk_bf16_f32 v74, v86, v84
	v_cvt_pk_bf16_f32 v75, v76, v75
	v_add_u32_e32 v76, 0xa0, v0
	v_mad_i64_i32 v[76:77], s[20:21], v76, s90, v[90:91]
	v_lshl_add_u64 v[126:127], v[76:77], 0, v[140:141]
	v_mov_b32_e32 v170, v74
	v_mov_b32_e32 v171, v75
	v_cndmask_b32_e64 v77, v88, v102, s[36:37]
	v_mov_b32_dpp v74, v70 row_ror:1 row_mask:0xf bank_mask:0xf
	v_mov_b32_dpp v76, v66 row_ror:1 row_mask:0xf bank_mask:0xf
	v_cndmask_b32_e64 v75, v74, v148, s[0:1]
	v_cndmask_b32_e64 v74, v76, v152, s[0:1]
	v_pk_mul_f32 v[74:75], v[190:191], v[74:75]
	v_cndmask_b32_e64 v76, v94, v98, s[36:37]
	v_pk_fma_f32 v[74:75], v[78:79], v[192:193], v[74:75]
	v_mov_b32_e32 v70, v67
	v_pk_fma_f32 v[74:75], v[194:195], v[76:77], v[74:75]
	v_cndmask_b32_e64 v77, v89, v103, s[36:37]
	v_pk_add_f32 v[74:75], v[196:197], v[74:75]
	v_cndmask_b32_e64 v76, v95, v99, s[36:37]
	v_mul_f32_e32 v66, 0xbfb8aa3b, v75
	v_exp_f32_e32 v66, v66
	v_mov_b32_dpp v82, v73 row_ror:1 row_mask:0xf bank_mask:0xf
	v_add_f32_e32 v66, 1.0, v66
	v_rcp_f32_e32 v66, v66
	v_mov_b32_dpp v84, v68 row_ror:1 row_mask:0xf bank_mask:0xf
	v_mov_b32_dpp v85, v69 row_ror:1 row_mask:0xf bank_mask:0xf
	v_add_u32_e32 v0, 0xb0, v0
	v_mul_f32_e32 v66, v75, v66
	v_mul_f32_e32 v78, v74, v66
	v_cndmask_b32_e64 v75, v80, v149, s[0:1]
	v_cndmask_b32_e64 v74, v83, v153, s[0:1]
	v_pk_mul_f32 v[74:75], v[106:107], v[74:75]
	v_mov_b32_e32 v106, 0
	v_pk_fma_f32 v[66:67], v[70:71], v[110:111], v[74:75]
	v_mov_b32_e32 v74, v68
	v_pk_fma_f32 v[66:67], v[114:115], v[76:77], v[66:67]
	v_mov_b32_e32 v75, v72
	v_pk_add_f32 v[66:67], v[118:119], v[66:67]
	v_cndmask_b32_e64 v71, v92, v104, s[36:37]
	v_mul_f32_e32 v70, 0xbfb8aa3b, v67
	v_exp_f32_e32 v70, v70
	v_mov_b32_e32 v72, v69
	s_and_b64 vcc, exec, s[42:43]
	v_mov_b32_e32 v110, 0
	v_add_f32_e32 v70, 1.0, v70
	v_rcp_f32_e32 v70, v70
	v_mov_b32_e32 v111, 0
	v_mul_f32_e32 v67, v67, v70
	v_mul_f32_e32 v76, v66, v67
	v_cndmask_b32_e64 v67, v81, v150, s[0:1]
	v_cndmask_b32_e64 v66, v84, v156, s[0:1]
	v_pk_mul_f32 v[66:67], v[142:143], v[66:67]
	v_cndmask_b32_e64 v70, v96, v100, s[36:37]
	v_pk_fma_f32 v[66:67], v[74:75], v[154:155], v[66:67]
	s_nop 0
	v_pk_fma_f32 v[66:67], v[158:159], v[70:71], v[66:67]
	v_cndmask_b32_e64 v71, v93, v105, s[36:37]
	v_pk_add_f32 v[66:67], v[162:163], v[66:67]
	v_cndmask_b32_e64 v70, v97, v101, s[36:37]
	v_mul_f32_e32 v68, 0xbfb8aa3b, v67
	v_exp_f32_e32 v68, v68
	s_nop 0
	v_add_f32_e32 v68, 1.0, v68
	v_rcp_f32_e32 v68, v68
	s_nop 0
	v_mul_f32_e32 v67, v67, v68
	v_mul_f32_e32 v68, v66, v67
	v_cndmask_b32_e64 v67, v82, v151, s[0:1]
	v_cndmask_b32_e64 v66, v85, v157, s[0:1]
	v_pk_mul_f32 v[66:67], v[108:109], v[66:67]
	s_nop 0
	v_pk_fma_f32 v[66:67], v[72:73], v[112:113], v[66:67]
	v_mov_b32_e32 v112, 0
	v_pk_fma_f32 v[66:67], v[116:117], v[70:71], v[66:67]
	v_mov_b32_e32 v113, 0
	v_pk_add_f32 v[66:67], v[120:121], v[66:67]
	s_nop 0
	v_mul_f32_e32 v69, 0xbfb8aa3b, v67
	v_exp_f32_e32 v69, v69
	s_nop 0
	v_add_f32_e32 v69, 1.0, v69
	v_rcp_f32_e32 v69, v69
	s_nop 0
	v_mul_f32_e32 v67, v67, v69
	v_mul_f32_e32 v67, v66, v67
	v_cvt_pk_bf16_f32 v66, v78, v76
	v_cvt_pk_bf16_f32 v67, v68, v67
	v_mad_i64_i32 v[68:69], s[20:21], v0, s90, v[90:91]
	v_lshl_add_u64 v[114:115], v[68:69], 0, v[140:141]
	v_mov_b32_e32 v174, v66
	v_mov_b32_e32 v175, v67
	v_or_b32_e32 v66, 4, v186
	v_ashrrev_i32_e32 v67, 31, v66
	v_lshlrev_b64 v[82:83], 2, v[66:67]
	v_lshl_add_u64 v[66:67], s[54:55], 0, v[82:83]
	v_lshl_add_u64 v[74:75], s[62:63], 0, v[82:83]
	v_lshl_add_u64 v[84:85], s[64:65], 0, v[82:83]
	global_load_dwordx4 v[70:73], v[188:189], off offset:16
	s_nop 0
	global_load_dwordx4 v[66:69], v[66:67], off
	s_nop 0
	global_load_dwordx4 v[74:77], v[74:75], off
	s_nop 0
	global_load_dwordx4 v[78:81], v[184:185], off offset:16
	global_load_dwordx4 v[98:101], v[84:85], off
	v_lshl_add_u64 v[84:85], s[66:67], 0, v[82:83]
	global_load_dwordx4 v[102:105], v[84:85], off
	v_lshl_add_u64 v[84:85], s[12:13], 0, v[82:83]
	v_lshl_add_u64 v[82:83], s[86:87], 0, v[82:83]
	global_load_dwordx4 v[94:97], v[84:85], off
	global_load_dwordx4 v[90:93], v[82:83], off
	s_cbranch_vccnz .LBB0_982
	ds_read_b128 v[110:113], v221

; __device__ __forceinline__ unsigned cvt_pk_bf16(float lo, float hi) { unsigned r; asm volatile("v_cvt_pk_bf16_f32 %0, %1, %2" : "=v"(r) : "v"(lo), "v"(hi)); return r; }
; __device__ __forceinline__ float sigmoidf_(float x) { return __builtin_amdgcn_rcpf(1.0f + __builtin_amdgcn_exp2f(-x * LOG2E)); }
; __device__ __forceinline__ f32x4 ror1v(const f32x4 v) { return (f32x4){dpp_ror1(v[0]), dpp_ror1(v[1]), dpp_ror1(v[2]), dpp_ror1(v[3])}; }
; __device__ __forceinline__ f32x4 rol1v(const f32x4 v) { return (f32x4){dpp_rol1(v[0]), dpp_rol1(v[1]), dpp_rol1(v[2]), dpp_rol1(v[3])}; }
;     __device__ __forceinline__ void operator()(const f32x4 (&acc)[2][2][4][2], const Unit& u, int wr, int wc, int fr, int fq) const {
;     ...
;                 for (int m = 0; m < 4; ++m) {
;                     const f32x4 cg_ = acc[ai][0][m][n], cv_ = acc[ai][1][m][n];
;                     const f32x4 ug0 = m > 0 ? ror1v(acc[ai][0][m - 1][n]) : hpg, uv0 = m > 0 ? ror1v(acc[ai][1][m - 1][n]) : hpv;
;                     const f32x4 dg0 = m < 3 ? rol1v(acc[ai][0][m + 1][n]) : hng, dv0 = m < 3 ? rol1v(acc[ai][1][m + 1][n]) : hnv;
;                     const f32x4 ug1 = ror1v(cg_), uv1 = ror1v(cv_), dg1 = rol1v(cg_), dv1 = rol1v(cv_);
;                     f32x4 ug, uv, dg, dv;
; #pragma unroll
;                     for (int e = 0; e < 4; ++e) { ug[e] = fr == 0 ? ug0[e] : ug1[e]; uv[e] = fr == 0 ? uv0[e] : uv1[e]; dg[e] = fr == 15 ? dg0[e] : dg1[e]; dv[e] = fr == 15 ? dv0[e] : dv1[e]; }
;                     const f32x4 gc = w0g * ug + w1g * cg_ + w2g * dg + bg, vc = w0v * uv + w1v * cv_ + w2v * dv + bv;
;                     f32x4 r;
; #pragma unroll
;                     for (int e = 0; e < 4; ++e) r[e] = gc[e] * sigmoidf_(gc[e]) * vc[e];
;                     u32x2 w; w.x = cvt_pk_bf16(r[0], r[1]); w.y = cvt_pk_bf16(r[2], r[3]);
;                     *(u32x2*)(ACT + (size_t)(u.pm * BM + ai * HALF + wr * 64 + m * 16 + fr) * FF + ch) = w;
.LBB0_988:
	v_mov_b32_dpp v0, v54 row_ror:15 row_mask:0xf bank_mask:0xf
	v_mov_b32_dpp v143, v50 row_ror:15 row_mask:0xf bank_mask:0xf
	v_mov_b32_dpp v147, v62 row_ror:1 row_mask:0xf bank_mask:0xf
	v_mov_b32_dpp v151, v58 row_ror:1 row_mask:0xf bank_mask:0xf
	v_mov_b32_dpp v116, v62 row_ror:15 row_mask:0xf bank_mask:0xf
	v_mov_b32_dpp v117, v58 row_ror:15 row_mask:0xf bank_mask:0xf
	s_waitcnt lgkmcnt(0)
	v_cndmask_b32_e64 v119, v147, v110, s[0:1]
	v_cndmask_b32_e64 v118, v151, v106, s[0:1]
	v_cndmask_b32_e64 v129, v116, v0, s[36:37]
	v_cndmask_b32_e64 v128, v117, v143, s[36:37]
	s_waitcnt vmcnt(3)
	v_mov_b32_e32 v116, v98
	v_mov_b32_e32 v117, v70
	v_pk_mul_f32 v[120:121], v[116:117], v[118:119]
	v_mov_b32_e32 v136, v58
	v_mov_b32_e32 v137, v62
	s_waitcnt vmcnt(2)
	v_mov_b32_e32 v118, v102
	v_mov_b32_e32 v119, v66
	v_pk_fma_f32 v[136:137], v[136:137], v[118:119], v[120:121]
	s_waitcnt vmcnt(1)
	v_mov_b32_e32 v120, v94
	v_mov_b32_e32 v121, v74
	v_pk_fma_f32 v[136:137], v[120:121], v[128:129], v[136:137]
	s_waitcnt vmcnt(0)
	v_mov_b32_e32 v128, v90
	v_mov_b32_e32 v129, v78
	v_pk_add_f32 v[136:137], v[128:129], v[136:137]
	v_mul_f32_e32 v58, 0xbfb8aa3b, v137
	v_exp_f32_e32 v58, v58
	v_mov_b32_dpp v148, v63 row_ror:1 row_mask:0xf bank_mask:0xf
	v_add_f32_e32 v58, 1.0, v58
	v_rcp_f32_e32 v58, v58
	v_mov_b32_dpp v152, v59 row_ror:1 row_mask:0xf bank_mask:0xf
	v_cndmask_b32_e64 v111, v148, v111, s[0:1]
	v_cndmask_b32_e64 v110, v152, v107, s[0:1]
	v_mov_b32_e32 v70, v99
	v_mov_b32_dpp v140, v55 row_ror:15 row_mask:0xf bank_mask:0xf
	v_mov_b32_dpp v144, v51 row_ror:15 row_mask:0xf bank_mask:0xf
	v_mov_b32_dpp v155, v63 row_ror:15 row_mask:0xf bank_mask:0xf
	v_mov_b32_dpp v158, v59 row_ror:15 row_mask:0xf bank_mask:0xf
	v_mul_f32_e32 v58, v137, v58
	v_pk_mul_f32 v[98:99], v[70:71], v[110:111]
	v_mov_b32_e32 v62, v59
	v_mov_b32_e32 v66, v103
	v_mul_f32_e32 v136, v136, v58
	v_cndmask_b32_e64 v107, v155, v140, s[36:37]
	v_cndmask_b32_e64 v106, v158, v144, s[36:37]
	v_pk_fma_f32 v[58:59], v[62:63], v[66:67], v[98:99]
	v_mov_b32_e32 v74, v95
	v_pk_fma_f32 v[58:59], v[74:75], v[106:107], v[58:59]
	v_mov_b32_e32 v78, v91
	v_pk_add_f32 v[58:59], v[78:79], v[58:59]
	v_mul_f32_e32 v62, 0xbfb8aa3b, v59
	v_exp_f32_e32 v62, v62
	v_mov_b32_dpp v149, v64 row_ror:1 row_mask:0xf bank_mask:0xf
	v_add_f32_e32 v62, 1.0, v62
	v_rcp_f32_e32 v62, v62
	v_mov_b32_dpp v153, v60 row_ror:1 row_mask:0xf bank_mask:0xf
	v_mul_f32_e32 v59, v59, v62
	v_mul_f32_e32 v106, v58, v59
	v_cndmask_b32_e64 v63, v149, v112, s[0:1]
	v_cndmask_b32_e64 v62, v153, v108, s[0:1]
	v_mov_b32_e32 v58, v100
	v_mov_b32_e32 v59, v72
	v_mov_b32_dpp v141, v56 row_ror:15 row_mask:0xf bank_mask:0xf
	v_mov_b32_dpp v145, v52 row_ror:15 row_mask:0xf bank_mask:0xf
	v_mov_b32_dpp v156, v64 row_ror:15 row_mask:0xf bank_mask:0xf
	v_mov_b32_dpp v159, v60 row_ror:15 row_mask:0xf bank_mask:0xf
	v_pk_mul_f32 v[90:91], v[58:59], v[62:63]
	v_mov_b32_e32 v98, v60
	v_mov_b32_e32 v99, v64
	v_mov_b32_e32 v62, v104
	v_mov_b32_e32 v63, v68
	v_cndmask_b32_e64 v95, v156, v141, s[36:37]
	v_cndmask_b32_e64 v94, v159, v145, s[36:37]
	v_pk_fma_f32 v[98:99], v[98:99], v[62:63], v[90:91]
	v_mov_b32_e32 v90, v96
	v_mov_b32_e32 v91, v76
	v_pk_fma_f32 v[98:99], v[90:91], v[94:95], v[98:99]
	v_mov_b32_e32 v94, v92
	v_mov_b32_e32 v95, v80
	v_pk_add_f32 v[98:99], v[94:95], v[98:99]
	v_mul_f32_e32 v60, 0xbfb8aa3b, v99
	v_exp_f32_e32 v60, v60
	v_mov_b32_dpp v150, v65 row_ror:1 row_mask:0xf bank_mask:0xf
	v_add_f32_e32 v60, 1.0, v60
	v_rcp_f32_e32 v60, v60
	v_mov_b32_dpp v154, v61 row_ror:1 row_mask:0xf bank_mask:0xf
	v_mul_f32_e32 v60, v99, v60
	v_mul_f32_e32 v92, v98, v60
	v_cndmask_b32_e64 v99, v150, v113, s[0:1]
	v_cndmask_b32_e64 v98, v154, v109, s[0:1]
	v_mov_b32_e32 v72, v101
	v_mov_b32_dpp v142, v57 row_ror:15 row_mask:0xf bank_mask:0xf
	v_mov_b32_dpp v146, v53 row_ror:15 row_mask:0xf bank_mask:0xf
	v_mov_b32_dpp v157, v65 row_ror:15 row_mask:0xf bank_mask:0xf
	v_mov_b32_dpp v160, v61 row_ror:15 row_mask:0xf bank_mask:0xf
	v_pk_mul_f32 v[98:99], v[72:73], v[98:99]
	v_mov_b32_e32 v64, v61
	v_mov_b32_e32 v68, v105
	v_cndmask_b32_e64 v103, v157, v142, s[36:37]
	v_cndmask_b32_e64 v102, v160, v146, s[36:37]
	v_pk_fma_f32 v[60:61], v[64:65], v[68:69], v[98:99]
	v_mov_b32_e32 v76, v97
	v_pk_fma_f32 v[60:61], v[76:77], v[102:103], v[60:61]
	v_mov_b32_e32 v80, v93
	v_pk_add_f32 v[60:61], v[80:81], v[60:61]
	v_mul_f32_e32 v64, 0xbfb8aa3b, v61
	v_exp_f32_e32 v64, v64
	v_mov_b32_dpp v104, v54 row_ror:1 row_mask:0xf bank_mask:0xf
	v_add_f32_e32 v64, 1.0, v64
	v_rcp_f32_e32 v64, v64
	v_mov_b32_dpp v108, v50 row_ror:1 row_mask:0xf bank_mask:0xf
	v_mov_b32_dpp v96, v46 row_ror:15 row_mask:0xf bank_mask:0xf
	v_mul_f32_e32 v61, v61, v64
	v_mul_f32_e32 v61, v60, v61
	v_cvt_pk_bf16_f32 v60, v136, v106
	v_cvt_pk_bf16_f32 v61, v92, v61
	v_mov_b32_e32 v248, v60
	v_mov_b32_e32 v249, v61
	global_store_dwordx4 v[138:139], v[246:249], off
	v_cndmask_b32_e64 v61, v104, v147, s[0:1]
	v_cndmask_b32_e64 v60, v108, v151, s[0:1]
	v_mov_b32_dpp v100, v42 row_ror:15 row_mask:0xf bank_mask:0xf
	v_pk_mul_f32 v[60:61], v[116:117], v[60:61]
	v_mov_b32_e32 v92, v50
	v_mov_b32_e32 v93, v54
	v_cndmask_b32_e64 v65, v0, v96, s[36:37]
	v_cndmask_b32_e64 v64, v143, v100, s[36:37]
	v_pk_fma_f32 v[60:61], v[92:93], v[118:119], v[60:61]
	v_pk_fma_f32 v[60:61], v[120:121], v[64:65], v[60:61]
	v_pk_add_f32 v[60:61], v[128:129], v[60:61]
	v_mov_b32_dpp v105, v55 row_ror:1 row_mask:0xf bank_mask:0xf
	v_mul_f32_e32 v0, 0xbfb8aa3b, v61
	v_exp_f32_e32 v0, v0
	v_mov_b32_dpp v109, v51 row_ror:1 row_mask:0xf bank_mask:0xf
	v_add_f32_e32 v0, 1.0, v0
	v_rcp_f32_e32 v0, v0
; __device__ __forceinline__ unsigned cvt_pk_bf16(float lo, float hi) { unsigned r; asm volatile("v_cvt_pk_bf16_f32 %0, %1, %2" : "=v"(r) : "v"(lo), "v"(hi)); return r; }
; __device__ __forceinline__ float sigmoidf_(float x) { return __builtin_amdgcn_rcpf(1.0f + __builtin_amdgcn_exp2f(-x * LOG2E)); }
; __device__ __forceinline__ f32x4 ror1v(const f32x4 v) { return (f32x4){dpp_ror1(v[0]), dpp_ror1(v[1]), dpp_ror1(v[2]), dpp_ror1(v[3])}; }
; __device__ __forceinline__ f32x4 rol1v(const f32x4 v) { return (f32x4){dpp_rol1(v[0]), dpp_rol1(v[1]), dpp_rol1(v[2]), dpp_rol1(v[3])}; }
;     __device__ __forceinline__ void operator()(const f32x4 (&acc)[2][2][4][2], const Unit& u, int wr, int wc, int fr, int fq) const {
;     ...
;                 for (int m = 0; m < 4; ++m) {
;                     const f32x4 cg_ = acc[ai][0][m][n], cv_ = acc[ai][1][m][n];
;                     const f32x4 ug0 = m > 0 ? ror1v(acc[ai][0][m - 1][n]) : hpg, uv0 = m > 0 ? ror1v(acc[ai][1][m - 1][n]) : hpv;
;                     const f32x4 dg0 = m < 3 ? rol1v(acc[ai][0][m + 1][n]) : hng, dv0 = m < 3 ? rol1v(acc[ai][1][m + 1][n]) : hnv;
;                     const f32x4 ug1 = ror1v(cg_), uv1 = ror1v(cv_), dg1 = rol1v(cg_), dv1 = rol1v(cv_);
;                     f32x4 ug, uv, dg, dv;
; #pragma unroll
;                     for (int e = 0; e < 4; ++e) { ug[e] = fr == 0 ? ug0[e] : ug1[e]; uv[e] = fr == 0 ? uv0[e] : uv1[e]; dg[e] = fr == 15 ? dg0[e] : dg1[e]; dv[e] = fr == 15 ? dv0[e] : dv1[e]; }
;                     const f32x4 gc = w0g * ug + w1g * cg_ + w2g * dg + bg, vc = w0v * uv + w1v * cv_ + w2v * dv + bv;
;                     f32x4 r;
; #pragma unroll
;                     for (int e = 0; e < 4; ++e) r[e] = gc[e] * sigmoidf_(gc[e]) * vc[e];
;                     u32x2 w; w.x = cvt_pk_bf16(r[0], r[1]); w.y = cvt_pk_bf16(r[2], r[3]);
;                     *(u32x2*)(ACT + (size_t)(u.pm * BM + ai * HALF + wr * 64 + m * 16 + fr) * FF + ch) = w;
	v_mov_b32_dpp v97, v47 row_ror:15 row_mask:0xf bank_mask:0xf
	v_mov_b32_dpp v101, v43 row_ror:15 row_mask:0xf bank_mask:0xf
	v_mov_b32_e32 v54, v51
	v_mul_f32_e32 v0, v61, v0
	v_mul_f32_e32 v0, v60, v0
	v_cndmask_b32_e64 v61, v105, v148, s[0:1]
	v_cndmask_b32_e64 v60, v109, v152, s[0:1]
	v_pk_mul_f32 v[60:61], v[70:71], v[60:61]
	v_cndmask_b32_e64 v65, v140, v97, s[36:37]
	v_cndmask_b32_e64 v64, v144, v101, s[36:37]
	v_pk_fma_f32 v[50:51], v[54:55], v[66:67], v[60:61]
	v_pk_fma_f32 v[50:51], v[74:75], v[64:65], v[50:51]
	v_pk_add_f32 v[50:51], v[78:79], v[50:51]
	v_mov_b32_dpp v106, v56 row_ror:1 row_mask:0xf bank_mask:0xf
	v_mul_f32_e32 v54, 0xbfb8aa3b, v51
	v_exp_f32_e32 v54, v54
	v_mov_b32_dpp v110, v52 row_ror:1 row_mask:0xf bank_mask:0xf
	v_add_f32_e32 v54, 1.0, v54
	v_rcp_f32_e32 v54, v54
	v_mov_b32_dpp v98, v48 row_ror:15 row_mask:0xf bank_mask:0xf
	v_mov_b32_dpp v102, v44 row_ror:15 row_mask:0xf bank_mask:0xf
	v_mov_b32_e32 v60, v52
	v_mul_f32_e32 v51, v51, v54
	v_mul_f32_e32 v64, v50, v51
	v_cndmask_b32_e64 v51, v106, v149, s[0:1]
	v_cndmask_b32_e64 v50, v110, v153, s[0:1]
	v_pk_mul_f32 v[50:51], v[58:59], v[50:51]
	v_mov_b32_e32 v61, v56
	v_cndmask_b32_e64 v55, v141, v98, s[36:37]
	v_cndmask_b32_e64 v54, v145, v102, s[36:37]
	v_pk_fma_f32 v[50:51], v[60:61], v[62:63], v[50:51]
	v_pk_fma_f32 v[50:51], v[90:91], v[54:55], v[50:51]
	v_pk_add_f32 v[50:51], v[94:95], v[50:51]
	v_mov_b32_dpp v107, v57 row_ror:1 row_mask:0xf bank_mask:0xf
	v_mul_f32_e32 v52, 0xbfb8aa3b, v51
	v_exp_f32_e32 v52, v52
	v_mov_b32_dpp v111, v53 row_ror:1 row_mask:0xf bank_mask:0xf
	v_add_f32_e32 v52, 1.0, v52
	v_rcp_f32_e32 v52, v52
	v_mov_b32_dpp v99, v49 row_ror:15 row_mask:0xf bank_mask:0xf
	v_mov_b32_dpp v103, v45 row_ror:15 row_mask:0xf bank_mask:0xf
	v_mov_b32_e32 v56, v53
	v_mul_f32_e32 v51, v51, v52
	v_mul_f32_e32 v52, v50, v51
	v_cndmask_b32_e64 v51, v107, v150, s[0:1]
	v_cndmask_b32_e64 v50, v111, v154, s[0:1]
	v_pk_mul_f32 v[50:51], v[72:73], v[50:51]
	v_cndmask_b32_e64 v55, v142, v99, s[36:37]
	v_cndmask_b32_e64 v54, v146, v103, s[36:37]
	v_pk_fma_f32 v[50:51], v[56:57], v[68:69], v[50:51]
	v_pk_fma_f32 v[50:51], v[76:77], v[54:55], v[50:51]
	v_pk_add_f32 v[50:51], v[80:81], v[50:51]
	v_mov_b32_dpp v93, v46 row_ror:1 row_mask:0xf bank_mask:0xf
	v_mul_f32_e32 v53, 0xbfb8aa3b, v51
	v_exp_f32_e32 v53, v53
	v_mov_b32_dpp v61, v34 row_ror:15 row_mask:0xf bank_mask:0xf
	v_mov_b32_e32 v54, v42
	v_mov_b32_e32 v55, v46
	v_add_f32_e32 v53, 1.0, v53
	v_rcp_f32_e32 v53, v53
	s_nop 0
	v_mul_f32_e32 v51, v51, v53
	v_mul_f32_e32 v51, v50, v51
	v_cvt_pk_bf16_f32 v50, v0, v64
	v_cvt_pk_bf16_f32 v51, v52, v51
	v_mov_b32_e32 v240, v50
	v_mov_b32_e32 v241, v51
	global_store_dwordx4 v[130:131], v[238:241], off
	v_cndmask_b32_e64 v51, v93, v104, s[0:1]
	v_mov_b32_dpp v131, v42 row_ror:1 row_mask:0xf bank_mask:0xf
	v_cndmask_b32_e64 v50, v131, v108, s[0:1]
	v_mov_b32_dpp v0, v38 row_ror:15 row_mask:0xf bank_mask:0xf
	v_pk_mul_f32 v[50:51], v[116:117], v[50:51]
	v_cndmask_b32_e64 v53, v96, v0, s[36:37]
	v_cndmask_b32_e64 v52, v100, v61, s[36:37]
	v_pk_fma_f32 v[50:51], v[54:55], v[118:119], v[50:51]
	v_mov_b32_dpp v112, v47 row_ror:1 row_mask:0xf bank_mask:0xf
	v_pk_fma_f32 v[50:51], v[120:121], v[52:53], v[50:51]
	v_mov_b32_dpp v136, v43 row_ror:1 row_mask:0xf bank_mask:0xf
	v_pk_add_f32 v[50:51], v[128:129], v[50:51]
	v_mul_f32_e32 v42, 0xbfb8aa3b, v51
	v_exp_f32_e32 v42, v42
	v_mov_b32_dpp v56, v39 row_ror:15 row_mask:0xf bank_mask:0xf
	v_mov_b32_dpp v64, v35 row_ror:15 row_mask:0xf bank_mask:0xf
	v_mov_b32_e32 v46, v43
	v_add_f32_e32 v42, 1.0, v42
	v_rcp_f32_e32 v42, v42
	v_cndmask_b32_e64 v53, v97, v56, s[36:37]
	v_cndmask_b32_e64 v52, v101, v64, s[36:37]
	v_mul_f32_e32 v42, v51, v42
	v_mul_f32_e32 v54, v50, v42
	v_cndmask_b32_e64 v51, v112, v105, s[0:1]
	v_cndmask_b32_e64 v50, v136, v109, s[0:1]
	v_pk_mul_f32 v[50:51], v[70:71], v[50:51]
	v_pk_fma_f32 v[42:43], v[46:47], v[66:67], v[50:51]
	v_mov_b32_dpp v113, v48 row_ror:1 row_mask:0xf bank_mask:0xf
	v_pk_fma_f32 v[42:43], v[74:75], v[52:53], v[42:43]
	v_mov_b32_dpp v137, v44 row_ror:1 row_mask:0xf bank_mask:0xf
	v_pk_add_f32 v[42:43], v[78:79], v[42:43]
	v_mul_f32_e32 v46, 0xbfb8aa3b, v43
	v_exp_f32_e32 v46, v46
	v_mov_b32_dpp v57, v40 row_ror:15 row_mask:0xf bank_mask:0xf
	v_mov_b32_e32 v50, v44
	v_add_f32_e32 v46, 1.0, v46
	v_rcp_f32_e32 v46, v46
	v_mov_b32_dpp v65, v36 row_ror:15 row_mask:0xf bank_mask:0xf
	v_mov_b32_e32 v51, v48
	v_cndmask_b32_e64 v47, v98, v57, s[36:37]
	v_mul_f32_e32 v43, v43, v46
	v_mul_f32_e32 v52, v42, v43
	v_cndmask_b32_e64 v43, v113, v106, s[0:1]
; #define LAS __attribute__((address_space(3)))
; __device__ __forceinline__ unsigned cvt_pk_bf16(float lo, float hi) { unsigned r; asm volatile("v_cvt_pk_bf16_f32 %0, %1, %2" : "=v"(r) : "v"(lo), "v"(hi)); return r; }
; __device__ __forceinline__ float sigmoidf_(float x) { return __builtin_amdgcn_rcpf(1.0f + __builtin_amdgcn_exp2f(-x * LOG2E)); }
; __device__ __forceinline__ f32x4 ror1v(const f32x4 v) { return (f32x4){dpp_ror1(v[0]), dpp_ror1(v[1]), dpp_ror1(v[2]), dpp_ror1(v[3])}; }
;     __device__ __forceinline__ void operator()(const f32x4 (&acc)[2][2][4][2], const Unit& u, int wr, int wc, int fr, int fq) const {
;     ...
;                 const f32x4 hpg = blk > 0 ? *(const LAS f32x4*)(xl + ((blk - 1) * 2 + 1) * 256 + colw + 4 * n) : z4;
;                 const f32x4 hpv = blk > 0 ? *(const LAS f32x4*)(xl + ((blk - 1) * 2 + 1) * 256 + 128 + colw + 4 * n) : z4;
;                 const f32x4 hng = blk < 3 ? *(const LAS f32x4*)(xl + ((blk + 1) * 2 + 0) * 256 + colw + 4 * n) : z4;
;                 const f32x4 hnv = blk < 3 ? *(const LAS f32x4*)(xl + ((blk + 1) * 2 + 0) * 256 + 128 + colw + 4 * n) : z4;
;     ...
;                 for (int m = 0; m < 4; ++m) {
;                     const f32x4 cg_ = acc[ai][0][m][n], cv_ = acc[ai][1][m][n];
;                     const f32x4 ug0 = m > 0 ? ror1v(acc[ai][0][m - 1][n]) : hpg, uv0 = m > 0 ? ror1v(acc[ai][1][m - 1][n]) : hpv;
;                     const f32x4 dg0 = m < 3 ? rol1v(acc[ai][0][m + 1][n]) : hng, dv0 = m < 3 ? rol1v(acc[ai][1][m + 1][n]) : hnv;
;                     const f32x4 ug1 = ror1v(cg_), uv1 = ror1v(cv_), dg1 = rol1v(cg_), dv1 = rol1v(cv_);
;                     f32x4 ug, uv, dg, dv;
; #pragma unroll
;                     for (int e = 0; e < 4; ++e) { ug[e] = fr == 0 ? ug0[e] : ug1[e]; uv[e] = fr == 0 ? uv0[e] : uv1[e]; dg[e] = fr == 15 ? dg0[e] : dg1[e]; dv[e] = fr == 15 ? dv0[e] : dv1[e]; }
;                     const f32x4 gc = w0g * ug + w1g * cg_ + w2g * dg + bg, vc = w0v * uv + w1v * cv_ + w2v * dv + bv;
;                     f32x4 r;
; #pragma unroll
;                     for (int e = 0; e < 4; ++e) r[e] = gc[e] * sigmoidf_(gc[e]) * vc[e];
;                     u32x2 w; w.x = cvt_pk_bf16(r[0], r[1]); w.y = cvt_pk_bf16(r[2], r[3]);
;                     *(u32x2*)(ACT + (size_t)(u.pm * BM + ai * HALF + wr * 64 + m * 16 + fr) * FF + ch) = w;
	v_cndmask_b32_e64 v42, v137, v110, s[0:1]
	v_pk_mul_f32 v[42:43], v[58:59], v[42:43]
	v_cndmask_b32_e64 v46, v102, v65, s[36:37]
	v_pk_fma_f32 v[42:43], v[50:51], v[62:63], v[42:43]
	v_pk_fma_f32 v[42:43], v[90:91], v[46:47], v[42:43]
	v_pk_add_f32 v[42:43], v[94:95], v[42:43]
	v_mov_b32_dpp v130, v49 row_ror:1 row_mask:0xf bank_mask:0xf
	v_mul_f32_e32 v44, 0xbfb8aa3b, v43
	v_exp_f32_e32 v44, v44
	v_mov_b32_dpp v138, v45 row_ror:1 row_mask:0xf bank_mask:0xf
	v_add_f32_e32 v44, 1.0, v44
	v_rcp_f32_e32 v44, v44
	v_mov_b32_dpp v60, v41 row_ror:15 row_mask:0xf bank_mask:0xf
	v_mov_b32_dpp v92, v37 row_ror:15 row_mask:0xf bank_mask:0xf
	v_mov_b32_e32 v48, v45
	v_mul_f32_e32 v43, v43, v44
	v_mul_f32_e32 v44, v42, v43
	v_cndmask_b32_e64 v43, v130, v107, s[0:1]
	v_cndmask_b32_e64 v42, v138, v111, s[0:1]
	v_pk_mul_f32 v[42:43], v[72:73], v[42:43]
	v_cndmask_b32_e64 v47, v99, v60, s[36:37]
	v_cndmask_b32_e64 v46, v103, v92, s[36:37]
	v_pk_fma_f32 v[42:43], v[48:49], v[68:69], v[42:43]
	v_pk_fma_f32 v[42:43], v[76:77], v[46:47], v[42:43]
	v_mov_b32_e32 v46, v34
	v_pk_add_f32 v[42:43], v[80:81], v[42:43]
	v_mov_b32_e32 v47, v38
	v_mul_f32_e32 v45, 0xbfb8aa3b, v43
	v_exp_f32_e32 v45, v45
	v_mov_b32_dpp v48, v39 row_ror:1 row_mask:0xf bank_mask:0xf
	v_add_f32_e32 v45, 1.0, v45
	v_rcp_f32_e32 v45, v45
	v_mov_b32_dpp v51, v35 row_ror:1 row_mask:0xf bank_mask:0xf
	v_mov_b32_dpp v49, v40 row_ror:1 row_mask:0xf bank_mask:0xf
	v_mul_f32_e32 v43, v43, v45
	v_mul_f32_e32 v43, v42, v43
	v_cvt_pk_bf16_f32 v42, v54, v52
	v_cvt_pk_bf16_f32 v43, v44, v43
	v_mov_b32_e32 v244, v42
	v_mov_b32_e32 v245, v43
	global_store_dwordx4 v[132:133], v[242:245], off
	v_cndmask_b32_e64 v45, v0, v86, s[36:37]
	v_mov_b32_dpp v42, v38 row_ror:1 row_mask:0xf bank_mask:0xf
	v_mov_b32_dpp v44, v34 row_ror:1 row_mask:0xf bank_mask:0xf
	v_cndmask_b32_e64 v43, v42, v93, s[0:1]
	v_cndmask_b32_e64 v42, v44, v131, s[0:1]
	v_pk_mul_f32 v[42:43], v[116:117], v[42:43]
	v_cndmask_b32_e64 v44, v61, v82, s[36:37]
	v_pk_fma_f32 v[42:43], v[46:47], v[118:119], v[42:43]
	v_mov_b32_e32 v38, v35
	v_pk_fma_f32 v[42:43], v[120:121], v[44:45], v[42:43]
	v_cndmask_b32_e64 v45, v56, v87, s[36:37]
	v_pk_add_f32 v[42:43], v[128:129], v[42:43]
	v_cndmask_b32_e64 v44, v64, v83, s[36:37]
	v_mul_f32_e32 v0, 0xbfb8aa3b, v43
	v_exp_f32_e32 v0, v0
	v_mov_b32_dpp v50, v41 row_ror:1 row_mask:0xf bank_mask:0xf
	v_add_f32_e32 v0, 1.0, v0
	v_rcp_f32_e32 v0, v0
	v_mov_b32_dpp v52, v36 row_ror:1 row_mask:0xf bank_mask:0xf
	v_mov_b32_dpp v53, v37 row_ror:1 row_mask:0xf bank_mask:0xf
	v_mul_f32_e32 v0, v43, v0
	v_mul_f32_e32 v0, v42, v0
	v_cndmask_b32_e64 v43, v48, v112, s[0:1]
	v_cndmask_b32_e64 v42, v51, v136, s[0:1]
	v_pk_mul_f32 v[42:43], v[70:71], v[42:43]
	s_and_b64 vcc, exec, s[46:47]
	v_pk_fma_f32 v[34:35], v[38:39], v[66:67], v[42:43]
	v_mov_b32_e32 v42, v36
	v_pk_fma_f32 v[34:35], v[74:75], v[44:45], v[34:35]
	v_mov_b32_e32 v43, v40
	v_pk_add_f32 v[34:35], v[78:79], v[34:35]
	v_cndmask_b32_e64 v39, v57, v88, s[36:37]
	v_mul_f32_e32 v38, 0xbfb8aa3b, v35
	v_exp_f32_e32 v38, v38
	v_mov_b32_e32 v40, v37
	v_mov_b32_e32 v46, 0
	v_mov_b32_e32 v47, 0
	v_add_f32_e32 v38, 1.0, v38
	v_rcp_f32_e32 v38, v38
	v_mov_b32_e32 v48, 0
	v_mul_f32_e32 v35, v35, v38
	v_mul_f32_e32 v44, v34, v35
	v_cndmask_b32_e64 v35, v49, v113, s[0:1]
	v_cndmask_b32_e64 v34, v52, v137, s[0:1]
	v_pk_mul_f32 v[34:35], v[58:59], v[34:35]
	v_cndmask_b32_e64 v38, v65, v84, s[36:37]
	v_pk_fma_f32 v[34:35], v[42:43], v[62:63], v[34:35]
	v_mov_b32_e32 v42, 0
	v_pk_fma_f32 v[34:35], v[90:91], v[38:39], v[34:35]
	v_cndmask_b32_e64 v39, v60, v89, s[36:37]
	v_pk_add_f32 v[34:35], v[94:95], v[34:35]
	v_cndmask_b32_e64 v38, v92, v85, s[36:37]
	v_mul_f32_e32 v36, 0xbfb8aa3b, v35
	v_exp_f32_e32 v36, v36
	v_mov_b32_e32 v49, 0
	v_add_f32_e32 v36, 1.0, v36
	v_rcp_f32_e32 v36, v36
	s_nop 0
	v_mul_f32_e32 v35, v35, v36
	v_mul_f32_e32 v36, v34, v35
	v_cndmask_b32_e64 v35, v50, v130, s[0:1]
	v_cndmask_b32_e64 v34, v53, v138, s[0:1]
	v_pk_mul_f32 v[34:35], v[72:73], v[34:35]
	s_nop 0
	v_pk_fma_f32 v[34:35], v[40:41], v[68:69], v[34:35]
	s_nop 0
	v_pk_fma_f32 v[34:35], v[76:77], v[38:39], v[34:35]
	s_nop 0
	v_pk_add_f32 v[34:35], v[80:81], v[34:35]
	s_nop 0
	v_mul_f32_e32 v37, 0xbfb8aa3b, v35
	v_exp_f32_e32 v37, v37
	s_nop 0
	v_add_f32_e32 v37, 1.0, v37
	v_rcp_f32_e32 v37, v37
	s_nop 0
	v_mul_f32_e32 v35, v35, v37
	v_mul_f32_e32 v35, v34, v35
	v_cvt_pk_bf16_f32 v34, v0, v44
	v_cvt_pk_bf16_f32 v35, v36, v35
	v_mov_b32_e32 v236, v34
	v_mov_b32_e32 v237, v35
	global_store_dwordx4 v[134:135], v[234:237], off
	s_cbranch_vccnz .LBB0_990
	ds_read_b128 v[46:49], v218 offset:3088

; __device__ __forceinline__ unsigned cvt_pk_bf16(float lo, float hi) { unsigned r; asm volatile("v_cvt_pk_bf16_f32 %0, %1, %2" : "=v"(r) : "v"(lo), "v"(hi)); return r; }
; __device__ __forceinline__ float sigmoidf_(float x) { return __builtin_amdgcn_rcpf(1.0f + __builtin_amdgcn_exp2f(-x * LOG2E)); }
; __device__ __forceinline__ f32x4 ror1v(const f32x4 v) { return (f32x4){dpp_ror1(v[0]), dpp_ror1(v[1]), dpp_ror1(v[2]), dpp_ror1(v[3])}; }
; __device__ __forceinline__ f32x4 rol1v(const f32x4 v) { return (f32x4){dpp_rol1(v[0]), dpp_rol1(v[1]), dpp_rol1(v[2]), dpp_rol1(v[3])}; }
;     __device__ __forceinline__ void operator()(const f32x4 (&acc)[2][2][4][2], const Unit& u, int wr, int wc, int fr, int fq) const {
;     ...
;                 for (int m = 0; m < 4; ++m) {
;                     const f32x4 cg_ = acc[ai][0][m][n], cv_ = acc[ai][1][m][n];
;                     const f32x4 ug0 = m > 0 ? ror1v(acc[ai][0][m - 1][n]) : hpg, uv0 = m > 0 ? ror1v(acc[ai][1][m - 1][n]) : hpv;
;                     const f32x4 dg0 = m < 3 ? rol1v(acc[ai][0][m + 1][n]) : hng, dv0 = m < 3 ? rol1v(acc[ai][1][m + 1][n]) : hnv;
;                     const f32x4 ug1 = ror1v(cg_), uv1 = ror1v(cv_), dg1 = rol1v(cg_), dv1 = rol1v(cv_);
;                     f32x4 ug, uv, dg, dv;
; #pragma unroll
;                     for (int e = 0; e < 4; ++e) { ug[e] = fr == 0 ? ug0[e] : ug1[e]; uv[e] = fr == 0 ? uv0[e] : uv1[e]; dg[e] = fr == 15 ? dg0[e] : dg1[e]; dv[e] = fr == 15 ? dv0[e] : dv1[e]; }
;                     const f32x4 gc = w0g * ug + w1g * cg_ + w2g * dg + bg, vc = w0v * uv + w1v * cv_ + w2v * dv + bv;
;                     f32x4 r;
; #pragma unroll
;                     for (int e = 0; e < 4; ++e) r[e] = gc[e] * sigmoidf_(gc[e]) * vc[e];
;                     u32x2 w; w.x = cvt_pk_bf16(r[0], r[1]); w.y = cvt_pk_bf16(r[2], r[3]);
;                     *(u32x2*)(ACT + (size_t)(u.pm * BM + ai * HALF + wr * 64 + m * 16 + fr) * FF + ch) = w;
.LBB0_996:
	v_mov_b32_dpp v83, v30 row_ror:1 row_mask:0xf bank_mask:0xf
	v_mov_b32_dpp v87, v26 row_ror:1 row_mask:0xf bank_mask:0xf
	v_mov_b32_dpp v0, v22 row_ror:15 row_mask:0xf bank_mask:0xf
	v_mov_b32_dpp v61, v18 row_ror:15 row_mask:0xf bank_mask:0xf
	v_mov_b32_dpp v52, v30 row_ror:15 row_mask:0xf bank_mask:0xf
	v_mov_b32_dpp v54, v26 row_ror:15 row_mask:0xf bank_mask:0xf
	s_waitcnt lgkmcnt(0)
	v_cndmask_b32_e64 v51, v83, v46, s[0:1]
	v_cndmask_b32_e64 v50, v87, v42, s[0:1]
	v_cndmask_b32_e64 v53, v52, v0, s[36:37]
	v_cndmask_b32_e64 v52, v54, v61, s[36:37]
	v_pk_mul_f32 v[50:51], v[116:117], v[50:51]
	v_mov_b32_e32 v54, v26
	v_mov_b32_e32 v55, v30
	v_pk_fma_f32 v[50:51], v[54:55], v[118:119], v[50:51]
	v_pk_fma_f32 v[50:51], v[120:121], v[52:53], v[50:51]
	v_pk_add_f32 v[50:51], v[128:129], v[50:51]
	v_mov_b32_dpp v84, v31 row_ror:1 row_mask:0xf bank_mask:0xf
	v_mul_f32_e32 v26, 0xbfb8aa3b, v51
	v_exp_f32_e32 v26, v26
	v_mov_b32_dpp v88, v27 row_ror:1 row_mask:0xf bank_mask:0xf
	v_cndmask_b32_e64 v47, v84, v47, s[0:1]
	v_cndmask_b32_e64 v46, v88, v43, s[0:1]
	v_mov_b32_dpp v56, v23 row_ror:15 row_mask:0xf bank_mask:0xf
	v_mov_b32_dpp v64, v19 row_ror:15 row_mask:0xf bank_mask:0xf
	v_mov_b32_dpp v93, v31 row_ror:15 row_mask:0xf bank_mask:0xf
	v_mov_b32_dpp v98, v27 row_ror:15 row_mask:0xf bank_mask:0xf
	v_add_f32_e32 v26, 1.0, v26
	v_pk_mul_f32 v[46:47], v[70:71], v[46:47]
	v_mov_b32_e32 v30, v27
	v_rcp_f32_e32 v54, v26
	v_cndmask_b32_e64 v43, v93, v56, s[36:37]
	v_cndmask_b32_e64 v42, v98, v64, s[36:37]
	v_pk_fma_f32 v[26:27], v[30:31], v[66:67], v[46:47]
	v_pk_fma_f32 v[26:27], v[74:75], v[42:43], v[26:27]
	v_pk_add_f32 v[26:27], v[78:79], v[26:27]
	v_mov_b32_dpp v85, v32 row_ror:1 row_mask:0xf bank_mask:0xf
	v_mul_f32_e32 v30, 0xbfb8aa3b, v27
	v_exp_f32_e32 v30, v30
	v_mov_b32_dpp v89, v28 row_ror:1 row_mask:0xf bank_mask:0xf
	v_mul_f32_e32 v31, v51, v54
	v_add_f32_e32 v30, 1.0, v30
	v_mul_f32_e32 v50, v50, v31
	v_rcp_f32_e32 v51, v30
	v_cndmask_b32_e64 v31, v85, v48, s[0:1]
	v_cndmask_b32_e64 v30, v89, v44, s[0:1]
	v_mov_b32_dpp v57, v24 row_ror:15 row_mask:0xf bank_mask:0xf
	v_mov_b32_dpp v65, v20 row_ror:15 row_mask:0xf bank_mask:0xf
	v_mov_b32_dpp v96, v32 row_ror:15 row_mask:0xf bank_mask:0xf
	v_mov_b32_dpp v52, v28 row_ror:15 row_mask:0xf bank_mask:0xf
	v_pk_mul_f32 v[30:31], v[58:59], v[30:31]
	v_mov_b32_e32 v46, v28
	v_mov_b32_e32 v47, v32
	v_cndmask_b32_e64 v43, v96, v57, s[36:37]
	v_cndmask_b32_e64 v42, v52, v65, s[36:37]
	v_pk_fma_f32 v[30:31], v[46:47], v[62:63], v[30:31]
	v_mov_b32_dpp v86, v33 row_ror:1 row_mask:0xf bank_mask:0xf
	v_mov_b32_dpp v92, v29 row_ror:1 row_mask:0xf bank_mask:0xf
	v_pk_fma_f32 v[30:31], v[90:91], v[42:43], v[30:31]
	v_pk_add_f32 v[30:31], v[94:95], v[30:31]
	v_cndmask_b32_e64 v43, v86, v49, s[0:1]
	v_cndmask_b32_e64 v42, v92, v45, s[0:1]
	v_mov_b32_dpp v60, v25 row_ror:15 row_mask:0xf bank_mask:0xf
	v_mov_b32_dpp v82, v21 row_ror:15 row_mask:0xf bank_mask:0xf
	v_mov_b32_dpp v97, v33 row_ror:15 row_mask:0xf bank_mask:0xf
	v_mov_b32_dpp v53, v29 row_ror:15 row_mask:0xf bank_mask:0xf
	v_mul_f32_e32 v28, 0xbfb8aa3b, v31
	v_pk_mul_f32 v[42:43], v[72:73], v[42:43]
	v_mov_b32_e32 v32, v29
	v_exp_f32_e32 v46, v28
	v_cndmask_b32_e64 v45, v97, v60, s[36:37]
	v_cndmask_b32_e64 v44, v53, v82, s[36:37]
	v_pk_fma_f32 v[28:29], v[32:33], v[68:69], v[42:43]
	v_add_f32_e32 v33, 1.0, v46
	v_pk_fma_f32 v[28:29], v[76:77], v[44:45], v[28:29]
	v_rcp_f32_e32 v33, v33
	v_pk_add_f32 v[28:29], v[80:81], v[28:29]
	v_mul_f32_e32 v27, v27, v51
	v_mul_f32_e32 v32, 0xbfb8aa3b, v29
	v_exp_f32_e32 v32, v32
	v_mul_f32_e32 v26, v26, v27
	v_mul_f32_e32 v27, v31, v33
	v_mul_f32_e32 v27, v30, v27
	v_add_f32_e32 v32, 1.0, v32
	v_rcp_f32_e32 v32, v32
	v_cvt_pk_bf16_f32 v26, v50, v26
	v_mul_f32_e32 v29, v29, v32
	v_mul_f32_e32 v28, v28, v29
	v_cvt_pk_bf16_f32 v27, v27, v28
	v_mov_b32_dpp v48, v22 row_ror:1 row_mask:0xf bank_mask:0xf
	v_mov_b32_dpp v52, v18 row_ror:1 row_mask:0xf bank_mask:0xf
	v_mov_b32_e32 v232, v26
	v_mov_b32_e32 v233, v27
	global_store_dwordx4 v[122:123], v[230:233], off
	v_cndmask_b32_e64 v27, v48, v83, s[0:1]
	v_cndmask_b32_e64 v26, v52, v87, s[0:1]
	v_mov_b32_dpp v32, v14 row_ror:15 row_mask:0xf bank_mask:0xf
	v_mov_b32_dpp v44, v10 row_ror:15 row_mask:0xf bank_mask:0xf
	v_pk_mul_f32 v[26:27], v[116:117], v[26:27]
	v_mov_b32_e32 v30, v18
	v_mov_b32_e32 v31, v22
	v_mov_b32_dpp v49, v23 row_ror:1 row_mask:0xf bank_mask:0xf
	v_mov_b32_dpp v53, v19 row_ror:1 row_mask:0xf bank_mask:0xf
	v_cndmask_b32_e64 v29, v0, v32, s[36:37]
	v_cndmask_b32_e64 v28, v61, v44, s[36:37]
	v_pk_fma_f32 v[26:27], v[30:31], v[118:119], v[26:27]
	v_pk_fma_f32 v[26:27], v[120:121], v[28:29], v[26:27]
	v_cndmask_b32_e64 v29, v49, v84, s[0:1]
	v_cndmask_b32_e64 v28, v53, v88, s[0:1]
	v_mov_b32_dpp v33, v15 row_ror:15 row_mask:0xf bank_mask:0xf
	v_mov_b32_dpp v45, v11 row_ror:15 row_mask:0xf bank_mask:0xf
	v_pk_add_f32 v[26:27], v[128:129], v[26:27]
	v_pk_mul_f32 v[28:29], v[70:71], v[28:29]
	v_mov_b32_e32 v22, v19
	v_mul_f32_e32 v0, 0xbfb8aa3b, v27
	v_cndmask_b32_e64 v31, v56, v33, s[36:37]
	v_cndmask_b32_e64 v30, v64, v45, s[36:37]
	v_pk_fma_f32 v[18:19], v[22:23], v[66:67], v[28:29]
	v_exp_f32_e32 v0, v0
	v_pk_fma_f32 v[18:19], v[74:75], v[30:31], v[18:19]
	v_pk_add_f32 v[18:19], v[78:79], v[18:19]
	v_add_f32_e32 v0, 1.0, v0
	v_mul_f32_e32 v22, 0xbfb8aa3b, v19
	v_exp_f32_e32 v22, v22
	v_rcp_f32_e32 v0, v0
	v_mov_b32_dpp v50, v24 row_ror:1 row_mask:0xf bank_mask:0xf
	v_add_f32_e32 v22, 1.0, v22
	v_mov_b32_dpp v54, v20 row_ror:1 row_mask:0xf bank_mask:0xf
	v_rcp_f32_e32 v30, v22
	v_cndmask_b32_e64 v23, v50, v85, s[0:1]
; __device__ __forceinline__ unsigned cvt_pk_bf16(float lo, float hi) { unsigned r; asm volatile("v_cvt_pk_bf16_f32 %0, %1, %2" : "=v"(r) : "v"(lo), "v"(hi)); return r; }
; __device__ __forceinline__ float sigmoidf_(float x) { return __builtin_amdgcn_rcpf(1.0f + __builtin_amdgcn_exp2f(-x * LOG2E)); }
; __device__ __forceinline__ f32x4 ror1v(const f32x4 v) { return (f32x4){dpp_ror1(v[0]), dpp_ror1(v[1]), dpp_ror1(v[2]), dpp_ror1(v[3])}; }
; __device__ __forceinline__ f32x4 rol1v(const f32x4 v) { return (f32x4){dpp_rol1(v[0]), dpp_rol1(v[1]), dpp_rol1(v[2]), dpp_rol1(v[3])}; }
;     __device__ __forceinline__ void operator()(const f32x4 (&acc)[2][2][4][2], const Unit& u, int wr, int wc, int fr, int fq) const {
;     ...
;                 for (int m = 0; m < 4; ++m) {
;                     const f32x4 cg_ = acc[ai][0][m][n], cv_ = acc[ai][1][m][n];
;                     const f32x4 ug0 = m > 0 ? ror1v(acc[ai][0][m - 1][n]) : hpg, uv0 = m > 0 ? ror1v(acc[ai][1][m - 1][n]) : hpv;
;                     const f32x4 dg0 = m < 3 ? rol1v(acc[ai][0][m + 1][n]) : hng, dv0 = m < 3 ? rol1v(acc[ai][1][m + 1][n]) : hnv;
;                     const f32x4 ug1 = ror1v(cg_), uv1 = ror1v(cv_), dg1 = rol1v(cg_), dv1 = rol1v(cv_);
;                     f32x4 ug, uv, dg, dv;
; #pragma unroll
;                     for (int e = 0; e < 4; ++e) { ug[e] = fr == 0 ? ug0[e] : ug1[e]; uv[e] = fr == 0 ? uv0[e] : uv1[e]; dg[e] = fr == 15 ? dg0[e] : dg1[e]; dv[e] = fr == 15 ? dv0[e] : dv1[e]; }
;                     const f32x4 gc = w0g * ug + w1g * cg_ + w2g * dg + bg, vc = w0v * uv + w1v * cv_ + w2v * dv + bv;
;                     f32x4 r;
; #pragma unroll
;                     for (int e = 0; e < 4; ++e) r[e] = gc[e] * sigmoidf_(gc[e]) * vc[e];
;                     u32x2 w; w.x = cvt_pk_bf16(r[0], r[1]); w.y = cvt_pk_bf16(r[2], r[3]);
;                     *(u32x2*)(ACT + (size_t)(u.pm * BM + ai * HALF + wr * 64 + m * 16 + fr) * FF + ch) = w;
	v_cndmask_b32_e64 v22, v54, v89, s[0:1]
	v_mov_b32_dpp v42, v16 row_ror:15 row_mask:0xf bank_mask:0xf
	v_mov_b32_dpp v46, v12 row_ror:15 row_mask:0xf bank_mask:0xf
	v_mul_f32_e32 v0, v27, v0
	v_pk_mul_f32 v[22:23], v[58:59], v[22:23]
	v_mov_b32_e32 v28, v20
	v_mov_b32_e32 v29, v24
	v_mul_f32_e32 v0, v26, v0
	v_cndmask_b32_e64 v27, v57, v42, s[36:37]
	v_cndmask_b32_e64 v26, v65, v46, s[36:37]
	v_pk_fma_f32 v[22:23], v[28:29], v[62:63], v[22:23]
	v_mov_b32_dpp v51, v25 row_ror:1 row_mask:0xf bank_mask:0xf
	v_mov_b32_dpp v55, v21 row_ror:1 row_mask:0xf bank_mask:0xf
	v_pk_fma_f32 v[22:23], v[90:91], v[26:27], v[22:23]
	v_pk_add_f32 v[22:23], v[94:95], v[22:23]
	v_cndmask_b32_e64 v27, v51, v86, s[0:1]
	v_cndmask_b32_e64 v26, v55, v92, s[0:1]
	v_mov_b32_dpp v43, v17 row_ror:15 row_mask:0xf bank_mask:0xf
	v_mov_b32_dpp v47, v13 row_ror:15 row_mask:0xf bank_mask:0xf
	v_mul_f32_e32 v20, 0xbfb8aa3b, v23
	v_pk_mul_f32 v[26:27], v[72:73], v[26:27]
	v_mov_b32_e32 v24, v21
	v_exp_f32_e32 v31, v20
	v_cndmask_b32_e64 v29, v60, v43, s[36:37]
	v_cndmask_b32_e64 v28, v82, v47, s[36:37]
	v_pk_fma_f32 v[20:21], v[24:25], v[68:69], v[26:27]
	v_add_f32_e32 v25, 1.0, v31
	v_pk_fma_f32 v[20:21], v[76:77], v[28:29], v[20:21]
	v_rcp_f32_e32 v25, v25
	v_pk_add_f32 v[20:21], v[80:81], v[20:21]
	v_mul_f32_e32 v19, v19, v30
	v_mul_f32_e32 v24, 0xbfb8aa3b, v21
	v_exp_f32_e32 v24, v24
	v_mul_f32_e32 v18, v18, v19
	v_mul_f32_e32 v19, v23, v25
	v_mul_f32_e32 v19, v22, v19
	v_add_f32_e32 v24, 1.0, v24
	v_rcp_f32_e32 v24, v24
	s_nop 0
	v_mul_f32_e32 v21, v21, v24
	v_mul_f32_e32 v20, v20, v21
	v_cvt_pk_bf16_f32 v18, v0, v18
	v_cvt_pk_bf16_f32 v19, v19, v20
	v_mov_b32_dpp v31, v14 row_ror:1 row_mask:0xf bank_mask:0xf
	v_mov_b32_dpp v61, v10 row_ror:1 row_mask:0xf bank_mask:0xf
	v_mov_b32_e32 v228, v18
	v_mov_b32_e32 v229, v19
	global_store_dwordx4 v[124:125], v[226:229], off
	v_cndmask_b32_e64 v19, v31, v48, s[0:1]
	v_cndmask_b32_e64 v18, v61, v52, s[0:1]
	v_mov_b32_dpp v0, v6 row_ror:15 row_mask:0xf bank_mask:0xf
	v_mov_b32_dpp v27, v2 row_ror:15 row_mask:0xf bank_mask:0xf
	v_pk_mul_f32 v[18:19], v[116:117], v[18:19]
	v_mov_b32_e32 v22, v10
	v_mov_b32_e32 v23, v14
	v_cndmask_b32_e64 v21, v32, v0, s[36:37]
	v_cndmask_b32_e64 v20, v44, v27, s[36:37]
	v_pk_fma_f32 v[18:19], v[22:23], v[118:119], v[18:19]
	v_pk_fma_f32 v[18:19], v[120:121], v[20:21], v[18:19]
	v_pk_add_f32 v[18:19], v[128:129], v[18:19]
	v_mov_b32_dpp v56, v15 row_ror:1 row_mask:0xf bank_mask:0xf
	v_mul_f32_e32 v10, 0xbfb8aa3b, v19
	v_exp_f32_e32 v10, v10
	v_mov_b32_dpp v64, v11 row_ror:1 row_mask:0xf bank_mask:0xf
	v_cndmask_b32_e64 v21, v56, v49, s[0:1]
	v_cndmask_b32_e64 v20, v64, v53, s[0:1]
	v_mov_b32_dpp v24, v7 row_ror:15 row_mask:0xf bank_mask:0xf
	v_mov_b32_dpp v28, v3 row_ror:15 row_mask:0xf bank_mask:0xf
	v_add_f32_e32 v10, 1.0, v10
	v_pk_mul_f32 v[20:21], v[70:71], v[20:21]
	v_mov_b32_e32 v14, v11
	v_rcp_f32_e32 v48, v10
	v_cndmask_b32_e64 v23, v33, v24, s[36:37]
	v_cndmask_b32_e64 v22, v45, v28, s[36:37]
	v_pk_fma_f32 v[10:11], v[14:15], v[66:67], v[20:21]
	v_pk_fma_f32 v[10:11], v[74:75], v[22:23], v[10:11]
	v_pk_add_f32 v[10:11], v[78:79], v[10:11]
	v_mov_b32_dpp v57, v16 row_ror:1 row_mask:0xf bank_mask:0xf
	v_mul_f32_e32 v14, 0xbfb8aa3b, v11
	v_exp_f32_e32 v14, v14
	v_mov_b32_dpp v32, v12 row_ror:1 row_mask:0xf bank_mask:0xf
	v_mul_f32_e32 v15, v19, v48
	v_add_f32_e32 v14, 1.0, v14
	v_mul_f32_e32 v22, v18, v15
	v_rcp_f32_e32 v23, v14
	v_cndmask_b32_e64 v15, v57, v50, s[0:1]
	v_cndmask_b32_e64 v14, v32, v54, s[0:1]
	v_mov_b32_dpp v25, v8 row_ror:15 row_mask:0xf bank_mask:0xf
	v_mov_b32_dpp v29, v4 row_ror:15 row_mask:0xf bank_mask:0xf
	v_pk_mul_f32 v[14:15], v[58:59], v[14:15]
	v_mov_b32_e32 v20, v12
	v_mov_b32_e32 v21, v16
	v_cndmask_b32_e64 v19, v42, v25, s[36:37]
	v_cndmask_b32_e64 v18, v46, v29, s[36:37]
	v_pk_fma_f32 v[14:15], v[20:21], v[62:63], v[14:15]
	v_mov_b32_dpp v60, v17 row_ror:1 row_mask:0xf bank_mask:0xf
	v_mov_b32_dpp v44, v13 row_ror:1 row_mask:0xf bank_mask:0xf
	v_pk_fma_f32 v[14:15], v[90:91], v[18:19], v[14:15]
	v_pk_add_f32 v[14:15], v[94:95], v[14:15]
	v_cndmask_b32_e64 v19, v60, v51, s[0:1]
; __device__ __forceinline__ unsigned cvt_pk_bf16(float lo, float hi) { unsigned r; asm volatile("v_cvt_pk_bf16_f32 %0, %1, %2" : "=v"(r) : "v"(lo), "v"(hi)); return r; }
; __device__ __forceinline__ float sigmoidf_(float x) { return __builtin_amdgcn_rcpf(1.0f + __builtin_amdgcn_exp2f(-x * LOG2E)); }
; #define PG8_BAR __builtin_amdgcn_s_barrier()
; template <class Epi, class Sched, bool ALIGN_EPI, bool SP2>
; __device__ __forceinline__ void gemm_phase(LAS unsigned char* lds, const int K, const Sched& S, const Epi& E) {
;     ...
;         PG8_WAIT_V(0);
;         if (!has_next) break;
;         if (!Epi::keep(cur)) {
; #pragma unroll
;         for (int a = 0; a < 2; ++a)
; #pragma unroll
;             for (int b = 0; b < 2; ++b)
; #pragma unroll
;                 for (int m = 0; m < 4; ++m)
; #pragma unroll
;                     for (int n = 0; n < 2; ++n) acc[a][b][m][n] = (f32x4){0.f, 0.f, 0.f, 0.f};
;         }
;         cur = nxt; cA = nA; cB = nB; ++ui;
;         if constexpr (ALIGN_EPI) { if (wr == 1) PG8_BAR; }
;     }
;     __device__ __forceinline__ void operator()(const f32x4 (&acc)[2][2][4][2], const Unit& u, int wr, int wc, int fr, int fq) const {
;     ...
;                 for (int m = 0; m < 4; ++m) {
;                     const f32x4 cg_ = acc[ai][0][m][n], cv_ = acc[ai][1][m][n];
;                     const f32x4 ug0 = m > 0 ? ror1v(acc[ai][0][m - 1][n]) : hpg, uv0 = m > 0 ? ror1v(acc[ai][1][m - 1][n]) : hpv;
;                     const f32x4 dg0 = m < 3 ? rol1v(acc[ai][0][m + 1][n]) : hng, dv0 = m < 3 ? rol1v(acc[ai][1][m + 1][n]) : hnv;
;                     const f32x4 ug1 = ror1v(cg_), uv1 = ror1v(cv_), dg1 = rol1v(cg_), dv1 = rol1v(cv_);
;                     f32x4 ug, uv, dg, dv;
; #pragma unroll
;                     for (int e = 0; e < 4; ++e) { ug[e] = fr == 0 ? ug0[e] : ug1[e]; uv[e] = fr == 0 ? uv0[e] : uv1[e]; dg[e] = fr == 15 ? dg0[e] : dg1[e]; dv[e] = fr == 15 ? dv0[e] : dv1[e]; }
;                     const f32x4 gc = w0g * ug + w1g * cg_ + w2g * dg + bg, vc = w0v * uv + w1v * cv_ + w2v * dv + bv;
;                     f32x4 r;
; #pragma unroll
;                     for (int e = 0; e < 4; ++e) r[e] = gc[e] * sigmoidf_(gc[e]) * vc[e];
;                     u32x2 w; w.x = cvt_pk_bf16(r[0], r[1]); w.y = cvt_pk_bf16(r[2], r[3]);
;                     *(u32x2*)(ACT + (size_t)(u.pm * BM + ai * HALF + wr * 64 + m * 16 + fr) * FF + ch) = w;
	v_cndmask_b32_e64 v18, v44, v55, s[0:1]
	v_mov_b32_dpp v26, v9 row_ror:15 row_mask:0xf bank_mask:0xf
	v_mov_b32_dpp v30, v5 row_ror:15 row_mask:0xf bank_mask:0xf
	v_mul_f32_e32 v12, 0xbfb8aa3b, v15
	v_pk_mul_f32 v[18:19], v[72:73], v[18:19]
	v_mov_b32_e32 v16, v13
	v_exp_f32_e32 v33, v12
	v_cndmask_b32_e64 v21, v43, v26, s[36:37]
	v_cndmask_b32_e64 v20, v47, v30, s[36:37]
	v_pk_fma_f32 v[12:13], v[16:17], v[68:69], v[18:19]
	v_add_f32_e32 v17, 1.0, v33
	v_pk_fma_f32 v[12:13], v[76:77], v[20:21], v[12:13]
	v_rcp_f32_e32 v17, v17
	v_pk_add_f32 v[12:13], v[80:81], v[12:13]
	v_mul_f32_e32 v11, v11, v23
	v_mul_f32_e32 v16, 0xbfb8aa3b, v13
	v_exp_f32_e32 v16, v16
	v_mul_f32_e32 v10, v10, v11
	v_mul_f32_e32 v11, v15, v17
	v_add_f32_e32 v16, 1.0, v16
	v_rcp_f32_e32 v16, v16
	v_mul_f32_e32 v11, v14, v11
	v_cvt_pk_bf16_f32 v10, v22, v10
	v_mul_f32_e32 v13, v13, v16
	v_mul_f32_e32 v12, v12, v13
	v_cvt_pk_bf16_f32 v11, v11, v12
	v_mov_b32_e32 v172, v10
	v_mov_b32_e32 v173, v11
	global_store_dwordx4 v[126:127], v[170:173], off
	v_mov_b32_dpp v10, v6 row_ror:1 row_mask:0xf bank_mask:0xf
	v_mov_b32_dpp v12, v2 row_ror:1 row_mask:0xf bank_mask:0xf
	v_cndmask_b32_e64 v11, v10, v31, s[0:1]
	v_cndmask_b32_e64 v10, v12, v61, s[0:1]
	v_pk_mul_f32 v[10:11], v[116:117], v[10:11]
	v_mov_b32_e32 v14, v2
	v_mov_b32_e32 v15, v6
	v_mov_b32_dpp v16, v7 row_ror:1 row_mask:0xf bank_mask:0xf
	v_mov_b32_dpp v19, v3 row_ror:1 row_mask:0xf bank_mask:0xf
	v_cndmask_b32_e64 v13, v0, v38, s[36:37]
	v_cndmask_b32_e64 v12, v27, v34, s[36:37]
	v_pk_fma_f32 v[10:11], v[14:15], v[118:119], v[10:11]
	v_mov_b32_e32 v6, v3
	v_pk_fma_f32 v[10:11], v[120:121], v[12:13], v[10:11]
	v_cndmask_b32_e64 v13, v16, v56, s[0:1]
	v_cndmask_b32_e64 v12, v19, v64, s[0:1]
	v_pk_add_f32 v[10:11], v[128:129], v[10:11]
	v_pk_mul_f32 v[12:13], v[70:71], v[12:13]
	v_mul_f32_e32 v0, 0xbfb8aa3b, v11
	v_cndmask_b32_e64 v15, v24, v39, s[36:37]
	v_cndmask_b32_e64 v14, v28, v35, s[36:37]
	v_pk_fma_f32 v[2:3], v[6:7], v[66:67], v[12:13]
	v_exp_f32_e32 v0, v0
	v_pk_fma_f32 v[2:3], v[74:75], v[14:15], v[2:3]
	v_pk_add_f32 v[2:3], v[78:79], v[2:3]
	v_add_f32_e32 v0, 1.0, v0
	v_mul_f32_e32 v6, 0xbfb8aa3b, v3
	v_exp_f32_e32 v6, v6
	v_rcp_f32_e32 v0, v0
	v_mov_b32_dpp v17, v8 row_ror:1 row_mask:0xf bank_mask:0xf
	v_add_f32_e32 v6, 1.0, v6
	v_mov_b32_dpp v20, v4 row_ror:1 row_mask:0xf bank_mask:0xf
	v_rcp_f32_e32 v14, v6
	v_cndmask_b32_e64 v7, v17, v57, s[0:1]
	v_cndmask_b32_e64 v6, v20, v32, s[0:1]
	v_mul_f32_e32 v0, v11, v0
	v_pk_mul_f32 v[6:7], v[58:59], v[6:7]
	v_mov_b32_e32 v12, v4
	v_mov_b32_e32 v13, v8
	v_mul_f32_e32 v0, v10, v0
	v_cndmask_b32_e64 v11, v25, v40, s[36:37]
	v_cndmask_b32_e64 v10, v29, v36, s[36:37]
	v_pk_fma_f32 v[6:7], v[12:13], v[62:63], v[6:7]
	v_mov_b32_dpp v18, v9 row_ror:1 row_mask:0xf bank_mask:0xf
	v_mov_b32_dpp v21, v5 row_ror:1 row_mask:0xf bank_mask:0xf
	v_pk_fma_f32 v[6:7], v[90:91], v[10:11], v[6:7]
	v_cndmask_b32_e64 v11, v18, v60, s[0:1]
	v_pk_add_f32 v[6:7], v[94:95], v[6:7]
	v_cndmask_b32_e64 v10, v21, v44, s[0:1]
	v_mul_f32_e32 v4, 0xbfb8aa3b, v7
	v_pk_mul_f32 v[10:11], v[72:73], v[10:11]
	v_mov_b32_e32 v8, v5
	v_exp_f32_e32 v15, v4
	v_cndmask_b32_e64 v13, v26, v41, s[36:37]
	v_cndmask_b32_e64 v12, v30, v37, s[36:37]
	v_pk_fma_f32 v[4:5], v[8:9], v[68:69], v[10:11]
	v_add_f32_e32 v9, 1.0, v15
	v_pk_fma_f32 v[4:5], v[76:77], v[12:13], v[4:5]
	v_rcp_f32_e32 v9, v9
	v_pk_add_f32 v[4:5], v[80:81], v[4:5]
	v_mul_f32_e32 v3, v3, v14
	v_mul_f32_e32 v8, 0xbfb8aa3b, v5
	v_exp_f32_e32 v8, v8
	v_mul_f32_e32 v2, v2, v3
	v_mul_f32_e32 v3, v7, v9
	v_mul_f32_e32 v3, v6, v3
	v_add_f32_e32 v8, 1.0, v8
	v_rcp_f32_e32 v8, v8
	v_cvt_pk_bf16_f32 v2, v0, v2
	s_andn2_b64 vcc, exec, s[26:27]
	v_mul_f32_e32 v5, v5, v8
	v_mul_f32_e32 v4, v4, v5
	v_cvt_pk_bf16_f32 v3, v3, v4
	v_mov_b32_e32 v176, v2
	v_mov_b32_e32 v177, v3
	global_store_dwordx4 v[114:115], v[174:177], off
	s_waitcnt vmcnt(0)
	s_mov_b64 s[24:25], -1
	s_cbranch_vccnz .LBB0_942
	v_readlane_b32 s20, v250, 17
	v_readlane_b32 s21, v250, 18
	s_andn2_b64 vcc, exec, s[20:21]
	s_cbranch_vccnz .LBB0_941
	s_barrier
	s_branch .LBB0_941
